# GEMM main loops: removed the per-phase s_setprio 1/0 flips around the MFMA clusters
# speedup vs baseline: 1.0200x; 1.0092x over previous
.LBB0_100:
	s_add_u32 s21, s48, 0xfff00080
	s_addc_u32 s28, s49, -1
	s_add_i32 s60, 0, 0x10000
	v_add_u32_e32 v124, s60, v175
	ds_read_b128 v[112:115], v124
	ds_read_b128 v[116:119], v124 offset:1024
	ds_read_b128 v[120:123], v124 offset:2048
	ds_read_b128 v[124:127], v124 offset:3072
	s_cmp_eq_u32 s20, 60
	s_cselect_b32 s51, s43, s28
	s_cselect_b32 s50, s24, s21
	s_cselect_b32 s29, s1, vcc_hi
	s_cselect_b32 s28, s25, vcc_lo
	v_lshl_add_u64 v[184:185], s[48:49], 0, v[158:159]
	s_add_i32 m0, s55, 0xc000
	ds_read_b128 v[128:131], v199
	ds_read_b128 v[132:135], v199 offset:1024
	ds_read_b128 v[162:165], v199 offset:2048
	ds_read_b128 v[166:169], v199 offset:3072
	ds_read_b128 v[170:173], v199 offset:4096
	ds_read_b128 v[200:203], v199 offset:5120
	ds_read_b128 v[204:207], v199 offset:6144
	ds_read_b128 v[208:211], v199 offset:7168
	global_load_lds_dwordx4 v[184:185], off
	v_lshl_add_u64 v[184:185], s[48:49], 0, v[160:161]
	s_add_i32 m0, s55, 0xe000
	s_nop 0
	global_load_lds_dwordx4 v[184:185], off
	s_waitcnt lgkmcnt(8)
	s_barrier
	s_waitcnt lgkmcnt(0)
	s_waitcnt lgkmcnt(0)
	v_mfma_f32_16x16x32_bf16 v[148:151], v[112:115], v[128:131], v[148:151]
	v_mfma_f32_16x16x32_bf16 v[144:147], v[120:123], v[128:131], v[144:147]
	v_mfma_f32_16x16x32_bf16 v[108:111], v[112:115], v[162:165], v[108:111]
	v_mfma_f32_16x16x32_bf16 v[104:107], v[120:123], v[162:165], v[104:107]
	v_mfma_f32_16x16x32_bf16 v[92:95], v[112:115], v[170:173], v[92:95]
	v_mfma_f32_16x16x32_bf16 v[88:91], v[120:123], v[170:173], v[88:91]
	v_mfma_f32_16x16x32_bf16 v[76:79], v[112:115], v[204:207], v[76:79]
	v_mfma_f32_16x16x32_bf16 v[72:75], v[120:123], v[204:207], v[72:75]
	v_mfma_f32_16x16x32_bf16 v[148:151], v[116:119], v[132:135], v[148:151]
	v_mfma_f32_16x16x32_bf16 v[144:147], v[124:127], v[132:135], v[144:147]
	v_mfma_f32_16x16x32_bf16 v[108:111], v[116:119], v[166:169], v[108:111]
	v_mfma_f32_16x16x32_bf16 v[104:107], v[124:127], v[166:169], v[104:107]
	v_mfma_f32_16x16x32_bf16 v[92:95], v[116:119], v[200:203], v[92:95]
	v_mfma_f32_16x16x32_bf16 v[88:91], v[124:127], v[200:203], v[88:91]
	v_mfma_f32_16x16x32_bf16 v[76:79], v[116:119], v[208:211], v[76:79]
	v_mfma_f32_16x16x32_bf16 v[72:75], v[124:127], v[208:211], v[72:75]
	s_barrier
	s_add_i32 s21, 0, 0x14000
	v_add_u32_e32 v184, s21, v175
	s_add_i32 s60, s60, s54
	ds_read_b128 v[212:215], v184
	ds_read_b128 v[216:219], v184 offset:1024
	ds_read_b128 v[232:235], v184 offset:2048
	ds_read_b128 v[236:239], v184 offset:3072
	v_lshl_add_u64 v[184:185], s[28:29], 0, v[176:177]
	s_mov_b32 m0, s60
	v_lshl_add_u64 v[192:193], s[28:29], 0, v[152:153]
	global_load_lds_dwordx4 v[184:185], off
	s_add_i32 m0, s60, 0x2000
	s_nop 0
	global_load_lds_dwordx4 v[192:193], off
	s_barrier
	s_waitcnt lgkmcnt(0)
	s_waitcnt lgkmcnt(0)
	v_mfma_f32_16x16x32_bf16 v[140:143], v[212:215], v[128:131], v[140:143]
	v_mfma_f32_16x16x32_bf16 v[100:103], v[212:215], v[162:165], v[100:103]
	v_mfma_f32_16x16x32_bf16 v[96:99], v[232:235], v[162:165], v[96:99]
	v_mfma_f32_16x16x32_bf16 v[84:87], v[212:215], v[170:173], v[84:87]
	v_mfma_f32_16x16x32_bf16 v[80:83], v[232:235], v[170:173], v[80:83]
	v_mfma_f32_16x16x32_bf16 v[68:71], v[212:215], v[204:207], v[68:71]
	v_mfma_f32_16x16x32_bf16 v[64:67], v[232:235], v[204:207], v[64:67]
	v_mfma_f32_16x16x32_bf16 v[140:143], v[216:219], v[132:135], v[140:143]
	v_mfma_f32_16x16x32_bf16 v[128:131], v[232:235], v[128:131], v[136:139]
	v_mfma_f32_16x16x32_bf16 v[100:103], v[216:219], v[166:169], v[100:103]
	v_mfma_f32_16x16x32_bf16 v[96:99], v[236:239], v[166:169], v[96:99]
	v_mfma_f32_16x16x32_bf16 v[84:87], v[216:219], v[200:203], v[84:87]
	v_mfma_f32_16x16x32_bf16 v[80:83], v[236:239], v[200:203], v[80:83]
	v_mfma_f32_16x16x32_bf16 v[68:71], v[216:219], v[208:211], v[68:71]
	v_mfma_f32_16x16x32_bf16 v[64:67], v[236:239], v[208:211], v[64:67]
	v_mfma_f32_16x16x32_bf16 v[128:131], v[236:239], v[132:135], v[128:131]
	s_mov_b32 m0, s55
	v_lshl_add_u64 v[194:195], s[50:51], 0, v[156:157]
	s_barrier
	ds_read_b128 v[132:135], v199 offset:16384
	ds_read_b128 v[136:139], v199 offset:17408
	ds_read_b128 v[162:165], v199 offset:18432
	ds_read_b128 v[166:169], v199 offset:19456
	ds_read_b128 v[170:173], v199 offset:20480
	ds_read_b128 v[200:203], v199 offset:21504
	ds_read_b128 v[204:207], v199 offset:22528
	ds_read_b128 v[208:211], v199 offset:23552
	global_load_lds_dwordx4 v[194:195], off
	v_lshl_add_u64 v[240:241], s[50:51], 0, v[154:155]
	s_mov_b32 m0, s56
	s_nop 0
	global_load_lds_dwordx4 v[240:241], off
	s_barrier
	s_waitcnt lgkmcnt(0)
	s_waitcnt lgkmcnt(0)
	v_mfma_f32_16x16x32_bf16 v[60:63], v[112:115], v[132:135], v[60:63]
	v_mfma_f32_16x16x32_bf16 v[56:59], v[120:123], v[132:135], v[56:59]
	v_mfma_f32_16x16x32_bf16 v[44:47], v[112:115], v[162:165], v[44:47]
	v_mfma_f32_16x16x32_bf16 v[40:43], v[120:123], v[162:165], v[40:43]
	v_mfma_f32_16x16x32_bf16 v[28:31], v[112:115], v[170:173], v[28:31]
	v_mfma_f32_16x16x32_bf16 v[24:27], v[120:123], v[170:173], v[24:27]
	v_mfma_f32_16x16x32_bf16 v[12:15], v[112:115], v[204:207], v[12:15]
	v_mfma_f32_16x16x32_bf16 v[8:11], v[120:123], v[204:207], v[8:11]
	v_mfma_f32_16x16x32_bf16 v[60:63], v[116:119], v[136:139], v[60:63]
	v_mfma_f32_16x16x32_bf16 v[56:59], v[124:127], v[136:139], v[56:59]
	v_mfma_f32_16x16x32_bf16 v[44:47], v[116:119], v[166:169], v[44:47]
	v_mfma_f32_16x16x32_bf16 v[40:43], v[124:127], v[166:169], v[40:43]
	v_mfma_f32_16x16x32_bf16 v[28:31], v[116:119], v[200:203], v[28:31]
	v_mfma_f32_16x16x32_bf16 v[24:27], v[124:127], v[200:203], v[24:27]
	v_mfma_f32_16x16x32_bf16 v[12:15], v[116:119], v[208:211], v[12:15]
	v_mfma_f32_16x16x32_bf16 v[8:11], v[124:127], v[208:211], v[8:11]
	s_barrier
	s_add_u32 s60, s28, 0x100000
	s_addc_u32 s61, s29, 0
	s_add_i32 s21, s21, s54
	v_lshl_add_u64 v[112:113], s[60:61], 0, v[176:177]
	s_mov_b32 m0, s21
	s_nop 0
	global_load_lds_dwordx4 v[112:113], off
	v_lshl_add_u64 v[112:113], s[60:61], 0, v[152:153]
	s_add_i32 m0, s21, 0x2000
	s_nop 0
	global_load_lds_dwordx4 v[112:113], off
	s_waitcnt vmcnt(6)
	s_barrier
	v_mfma_f32_16x16x32_bf16 v[52:55], v[212:215], v[132:135], v[52:55]
	v_mfma_f32_16x16x32_bf16 v[48:51], v[232:235], v[132:135], v[48:51]
	v_mfma_f32_16x16x32_bf16 v[36:39], v[212:215], v[162:165], v[36:39]
	v_mfma_f32_16x16x32_bf16 v[32:35], v[232:235], v[162:165], v[32:35]
	v_mfma_f32_16x16x32_bf16 v[20:23], v[212:215], v[170:173], v[20:23]
	v_mfma_f32_16x16x32_bf16 v[16:19], v[232:235], v[170:173], v[16:19]
	v_mfma_f32_16x16x32_bf16 v[4:7], v[212:215], v[204:207], v[4:7]
	v_mfma_f32_16x16x32_bf16 v[0:3], v[232:235], v[204:207], v[0:3]
	v_mfma_f32_16x16x32_bf16 v[52:55], v[216:219], v[136:139], v[52:55]
	v_mfma_f32_16x16x32_bf16 v[48:51], v[236:239], v[136:139], v[48:51]
	v_mfma_f32_16x16x32_bf16 v[36:39], v[216:219], v[166:169], v[36:39]
	v_mfma_f32_16x16x32_bf16 v[32:35], v[236:239], v[166:169], v[32:35]
	v_mfma_f32_16x16x32_bf16 v[20:23], v[216:219], v[200:203], v[20:23]
	v_mfma_f32_16x16x32_bf16 v[16:19], v[236:239], v[200:203], v[16:19]
	v_mfma_f32_16x16x32_bf16 v[4:7], v[216:219], v[208:211], v[4:7]
	v_mfma_f32_16x16x32_bf16 v[0:3], v[236:239], v[208:211], v[0:3]
	s_add_i32 s21, 0, 0x18000
	v_add_u32_e32 v124, s21, v175
	s_barrier
	ds_read_b128 v[112:115], v124
	ds_read_b128 v[116:119], v124 offset:1024
	ds_read_b128 v[120:123], v124 offset:2048
	ds_read_b128 v[124:127], v124 offset:3072
	s_add_u32 s50, s50, 0x100000
	s_addc_u32 s51, s51, 0
	s_mov_b32 m0, s57
	v_lshl_add_u64 v[212:213], s[50:51], 0, v[156:157]
	ds_read_b128 v[132:135], v199 offset:32768
	ds_read_b128 v[136:139], v199 offset:33792
	ds_read_b128 v[162:165], v199 offset:34816
	ds_read_b128 v[166:169], v199 offset:35840
	ds_read_b128 v[170:173], v199 offset:36864
	ds_read_b128 v[200:203], v199 offset:37888
	ds_read_b128 v[204:207], v199 offset:38912
	ds_read_b128 v[208:211], v199 offset:39936
	global_load_lds_dwordx4 v[212:213], off
	v_lshl_add_u64 v[212:213], s[50:51], 0, v[154:155]
	s_mov_b32 m0, s58
	s_nop 0
	global_load_lds_dwordx4 v[212:213], off
	s_waitcnt lgkmcnt(8)
	s_barrier
	s_waitcnt lgkmcnt(0)
	s_waitcnt lgkmcnt(0)
	v_mfma_f32_16x16x32_bf16 v[148:151], v[112:115], v[132:135], v[148:151]
	v_mfma_f32_16x16x32_bf16 v[144:147], v[120:123], v[132:135], v[144:147]
	v_mfma_f32_16x16x32_bf16 v[108:111], v[112:115], v[162:165], v[108:111]
	v_mfma_f32_16x16x32_bf16 v[104:107], v[120:123], v[162:165], v[104:107]
	v_mfma_f32_16x16x32_bf16 v[92:95], v[112:115], v[170:173], v[92:95]
	v_mfma_f32_16x16x32_bf16 v[88:91], v[120:123], v[170:173], v[88:91]
	v_mfma_f32_16x16x32_bf16 v[76:79], v[112:115], v[204:207], v[76:79]
	v_mfma_f32_16x16x32_bf16 v[72:75], v[120:123], v[204:207], v[72:75]
	v_mfma_f32_16x16x32_bf16 v[148:151], v[116:119], v[136:139], v[148:151]
	v_mfma_f32_16x16x32_bf16 v[144:147], v[124:127], v[136:139], v[144:147]
	v_mfma_f32_16x16x32_bf16 v[108:111], v[116:119], v[166:169], v[108:111]
	v_mfma_f32_16x16x32_bf16 v[104:107], v[124:127], v[166:169], v[104:107]
	v_mfma_f32_16x16x32_bf16 v[92:95], v[116:119], v[200:203], v[92:95]
	v_mfma_f32_16x16x32_bf16 v[88:91], v[124:127], v[200:203], v[88:91]
	v_mfma_f32_16x16x32_bf16 v[76:79], v[116:119], v[208:211], v[76:79]
	v_mfma_f32_16x16x32_bf16 v[72:75], v[124:127], v[208:211], v[72:75]
	s_barrier
	s_add_i32 s50, 0, 0x1c000
	s_add_i32 s21, s21, s54
	v_add_u32_e32 v231, s50, v175
	v_lshl_add_u64 v[184:185], v[184:185], 0, s[52:53]
	s_mov_b32 m0, s21
	ds_read_b128 v[212:215], v231
	ds_read_b128 v[216:219], v231 offset:1024
	ds_read_b128 v[232:235], v231 offset:2048
	ds_read_b128 v[236:239], v231 offset:3072
	global_load_lds_dwordx4 v[184:185], off
	v_lshl_add_u64 v[184:185], v[192:193], 0, s[52:53]
	s_add_i32 m0, s21, 0x2000
	s_nop 0
	global_load_lds_dwordx4 v[184:185], off
	s_barrier
	s_waitcnt lgkmcnt(0)
	s_waitcnt lgkmcnt(0)
	v_mfma_f32_16x16x32_bf16 v[140:143], v[212:215], v[132:135], v[140:143]
	v_mfma_f32_16x16x32_bf16 v[128:131], v[232:235], v[132:135], v[128:131]
	v_mfma_f32_16x16x32_bf16 v[100:103], v[212:215], v[162:165], v[100:103]
	v_mfma_f32_16x16x32_bf16 v[96:99], v[232:235], v[162:165], v[96:99]
	v_mfma_f32_16x16x32_bf16 v[84:87], v[212:215], v[170:173], v[84:87]
	v_mfma_f32_16x16x32_bf16 v[80:83], v[232:235], v[170:173], v[80:83]
	v_mfma_f32_16x16x32_bf16 v[68:71], v[212:215], v[204:207], v[68:71]
	v_mfma_f32_16x16x32_bf16 v[64:67], v[232:235], v[204:207], v[64:67]
	v_mfma_f32_16x16x32_bf16 v[140:143], v[216:219], v[136:139], v[140:143]
	v_mfma_f32_16x16x32_bf16 v[136:139], v[236:239], v[136:139], v[128:131]
	v_mfma_f32_16x16x32_bf16 v[100:103], v[216:219], v[166:169], v[100:103]
	v_mfma_f32_16x16x32_bf16 v[96:99], v[236:239], v[166:169], v[96:99]
	v_mfma_f32_16x16x32_bf16 v[84:87], v[216:219], v[200:203], v[84:87]
	v_mfma_f32_16x16x32_bf16 v[80:83], v[236:239], v[200:203], v[80:83]
	v_mfma_f32_16x16x32_bf16 v[68:71], v[216:219], v[208:211], v[68:71]
	v_mfma_f32_16x16x32_bf16 v[64:67], v[236:239], v[208:211], v[64:67]
	s_mov_b32 m0, s7
	v_lshl_add_u64 v[184:185], v[194:195], 0, s[52:53]
	s_barrier
	ds_read_b128 v[128:131], v199 offset:49152
	ds_read_b128 v[132:135], v199 offset:50176
	ds_read_b128 v[162:165], v199 offset:51200
	ds_read_b128 v[166:169], v199 offset:52224
	ds_read_b128 v[170:173], v199 offset:53248
	ds_read_b128 v[200:203], v199 offset:54272
	ds_read_b128 v[204:207], v199 offset:55296
	ds_read_b128 v[208:211], v199 offset:56320
	global_load_lds_dwordx4 v[184:185], off
	v_lshl_add_u64 v[184:185], v[240:241], 0, s[52:53]
	s_mov_b32 m0, s15
	s_nop 0
	global_load_lds_dwordx4 v[184:185], off
	s_barrier
	s_waitcnt lgkmcnt(0)
	s_waitcnt lgkmcnt(0)
	v_mfma_f32_16x16x32_bf16 v[60:63], v[112:115], v[128:131], v[60:63]
	v_mfma_f32_16x16x32_bf16 v[56:59], v[120:123], v[128:131], v[56:59]
	v_mfma_f32_16x16x32_bf16 v[44:47], v[112:115], v[162:165], v[44:47]
	v_mfma_f32_16x16x32_bf16 v[40:43], v[120:123], v[162:165], v[40:43]
	v_mfma_f32_16x16x32_bf16 v[28:31], v[112:115], v[170:173], v[28:31]
	v_mfma_f32_16x16x32_bf16 v[24:27], v[120:123], v[170:173], v[24:27]
	v_mfma_f32_16x16x32_bf16 v[12:15], v[112:115], v[204:207], v[12:15]
	v_mfma_f32_16x16x32_bf16 v[8:11], v[120:123], v[204:207], v[8:11]
	v_mfma_f32_16x16x32_bf16 v[60:63], v[116:119], v[132:135], v[60:63]
	v_mfma_f32_16x16x32_bf16 v[56:59], v[124:127], v[132:135], v[56:59]
	v_mfma_f32_16x16x32_bf16 v[44:47], v[116:119], v[166:169], v[44:47]
	v_mfma_f32_16x16x32_bf16 v[40:43], v[124:127], v[166:169], v[40:43]
	v_mfma_f32_16x16x32_bf16 v[28:31], v[116:119], v[200:203], v[28:31]
	v_mfma_f32_16x16x32_bf16 v[24:27], v[124:127], v[200:203], v[24:27]
	v_mfma_f32_16x16x32_bf16 v[12:15], v[116:119], v[208:211], v[12:15]
	v_mfma_f32_16x16x32_bf16 v[8:11], v[124:127], v[208:211], v[8:11]
	s_barrier
	s_add_u32 s28, s28, 0x100080
	s_addc_u32 s29, s29, 0
	s_add_i32 s21, s50, s54
	v_lshl_add_u64 v[112:113], s[28:29], 0, v[176:177]
	s_mov_b32 m0, s21
	s_nop 0
	global_load_lds_dwordx4 v[112:113], off
	v_lshl_add_u64 v[112:113], s[28:29], 0, v[152:153]
	s_add_i32 m0, s21, 0x2000
	s_nop 0
	global_load_lds_dwordx4 v[112:113], off
	s_waitcnt vmcnt(6)
	s_barrier
	v_mfma_f32_16x16x32_bf16 v[52:55], v[212:215], v[128:131], v[52:55]
	v_mfma_f32_16x16x32_bf16 v[48:51], v[232:235], v[128:131], v[48:51]
	v_mfma_f32_16x16x32_bf16 v[36:39], v[212:215], v[162:165], v[36:39]
	v_mfma_f32_16x16x32_bf16 v[32:35], v[232:235], v[162:165], v[32:35]
	v_mfma_f32_16x16x32_bf16 v[20:23], v[212:215], v[170:173], v[20:23]
	v_mfma_f32_16x16x32_bf16 v[16:19], v[232:235], v[170:173], v[16:19]
	v_mfma_f32_16x16x32_bf16 v[4:7], v[212:215], v[204:207], v[4:7]
	v_mfma_f32_16x16x32_bf16 v[0:3], v[232:235], v[204:207], v[0:3]
	v_mfma_f32_16x16x32_bf16 v[52:55], v[216:219], v[132:135], v[52:55]
	v_mfma_f32_16x16x32_bf16 v[48:51], v[236:239], v[132:135], v[48:51]
	v_mfma_f32_16x16x32_bf16 v[36:39], v[216:219], v[166:169], v[36:39]
	v_mfma_f32_16x16x32_bf16 v[32:35], v[236:239], v[166:169], v[32:35]
	v_mfma_f32_16x16x32_bf16 v[20:23], v[216:219], v[200:203], v[20:23]
	v_mfma_f32_16x16x32_bf16 v[16:19], v[236:239], v[200:203], v[16:19]
	v_mfma_f32_16x16x32_bf16 v[4:7], v[216:219], v[208:211], v[4:7]
	v_mfma_f32_16x16x32_bf16 v[0:3], v[236:239], v[208:211], v[0:3]
	s_add_i32 s20, s20, 2
	s_add_u32 s48, s48, 0x100
	s_addc_u32 s49, s49, 0
	s_add_u32 vcc_lo, vcc_lo, 0x100
	s_addc_u32 vcc_hi, vcc_hi, 0
	s_cmp_gt_u32 s20, 61
	s_barrier
	s_cbranch_scc0 .LBB0_100
	v_lshl_or_b32 v162, s34, 8, v198
	v_lshl_add_u32 v166, s2, 8, v174
	v_ashrrev_i32_e32 v163, 31, v162
	v_lshlrev_b64 v[184:185], 1, v[162:163]
	v_ashrrev_i32_e32 v167, 31, v166
	v_lshl_add_u64 v[164:165], s[68:69], 0, v[184:185]
	v_lshlrev_b64 v[192:193], 11, v[166:167]
	v_lshl_add_u64 v[112:113], v[164:165], 0, v[192:193]
	global_load_dwordx4 v[200:203], v[112:113], off
	global_load_dwordx4 v[204:207], v[112:113], off offset:256
	v_or_b32_e32 v172, 16, v166
	v_ashrrev_i32_e32 v173, 31, v172
	v_lshlrev_b64 v[112:113], 11, v[172:173]
	v_or_b32_e32 v170, 32, v166
	v_lshl_add_u64 v[112:113], v[164:165], 0, v[112:113]
	v_ashrrev_i32_e32 v171, 31, v170
	global_load_dwordx4 v[132:135], v[112:113], off
	global_load_dwordx4 v[128:131], v[112:113], off offset:256
	v_lshlrev_b64 v[112:113], 11, v[170:171]
	v_or_b32_e32 v168, 48, v166
	v_lshl_add_u64 v[112:113], v[164:165], 0, v[112:113]
	v_ashrrev_i32_e32 v169, 31, v168
	global_load_dwordx4 v[124:127], v[112:113], off
	global_load_dwordx4 v[120:123], v[112:113], off offset:256
	v_lshlrev_b64 v[112:113], 11, v[168:169]
	v_lshl_add_u64 v[112:113], v[164:165], 0, v[112:113]
	global_load_dwordx4 v[116:119], v[112:113], off
	s_nop 0
	global_load_dwordx4 v[112:115], v[112:113], off offset:256
	v_add_u32_e32 v214, 0x80, v166
	v_ashrrev_i32_e32 v215, 31, v214
	v_lshlrev_b64 v[214:215], 11, v[214:215]
	v_lshl_add_u64 v[214:215], v[164:165], 0, v[214:215]
	global_load_dwordx4 v[208:211], v[214:215], off
	s_nop 0
	global_load_dwordx4 v[212:215], v[214:215], off offset:256
	v_add_u32_e32 v234, 0x90, v166
	v_ashrrev_i32_e32 v235, 31, v234
	v_lshlrev_b64 v[234:235], 11, v[234:235]
	v_lshl_add_u64 v[234:235], v[164:165], 0, v[234:235]
	global_load_dwordx4 v[216:219], v[234:235], off
	s_nop 0
	global_load_dwordx4 v[232:235], v[234:235], off offset:256
	v_add_u32_e32 v242, 0xa0, v166
	v_ashrrev_i32_e32 v243, 31, v242
	v_lshlrev_b64 v[242:243], 11, v[242:243]
	v_lshl_add_u64 v[242:243], v[164:165], 0, v[242:243]
	global_load_dwordx4 v[236:239], v[242:243], off
	s_nop 0
	global_load_dwordx4 v[240:243], v[242:243], off offset:256
	v_add_u32_e32 v250, 0xb0, v166
	v_ashrrev_i32_e32 v251, 31, v250
	v_lshlrev_b64 v[250:251], 11, v[250:251]
	v_lshl_add_u64 v[250:251], v[164:165], 0, v[250:251]
	global_load_dwordx4 v[244:247], v[250:251], off
	s_nop 0
	global_load_dwordx4 v[248:251], v[250:251], off offset:256
	s_lshl_b32 s48, s34, 2
	s_ashr_i32 s49, s48, 31
	s_waitcnt vmcnt(8)
	v_lshlrev_b32_e32 v194, 16, v200
	v_add_f32_e32 v148, v148, v194
	v_and_b32_e32 v194, 0xffff0000, v200
	v_add_f32_e32 v149, v149, v194
	v_lshlrev_b32_e32 v194, 16, v201
	v_add_f32_e32 v150, v150, v194
	v_and_b32_e32 v194, 0xffff0000, v201
	v_add_f32_e32 v151, v151, v194
	v_lshlrev_b32_e32 v194, 16, v202
	v_add_f32_e32 v194, v144, v194
	v_and_b32_e32 v144, 0xffff0000, v202
	v_add_f32_e32 v195, v145, v144
	v_lshlrev_b32_e32 v144, 16, v203
	v_add_f32_e32 v200, v146, v144
	v_and_b32_e32 v144, 0xffff0000, v203
	v_add_f32_e32 v147, v147, v144
	v_mul_f32_e32 v144, v194, v194
	v_mul_f32_e32 v145, v195, v195
	v_fmac_f32_e32 v144, v148, v148
	v_fmac_f32_e32 v145, v149, v149
	v_add_f32_e32 v144, v144, v145
	v_mul_f32_e32 v145, v200, v200
	v_fmac_f32_e32 v145, v150, v150
	v_add_f32_e32 v144, v145, v144
	v_mul_f32_e32 v145, v147, v147
	v_fmac_f32_e32 v145, v151, v151
	v_add_f32_e32 v201, v145, v144
	v_cvt_pk_bf16_f32 v144, v148, v149
	v_lshl_add_u64 v[148:149], s[64:65], 0, v[192:193]
	v_lshl_add_u64 v[148:149], v[148:149], 0, v[184:185]
	v_cvt_pk_bf16_f32 v145, v150, v151
	v_cvt_pk_bf16_f32 v146, v194, v195
	v_cvt_pk_bf16_f32 v147, v200, v147
	global_store_dwordx4 v[148:149], v[144:147], off
	s_nop 1
	v_lshlrev_b32_e32 v144, 16, v204
	v_add_f32_e32 v140, v140, v144
	v_and_b32_e32 v144, 0xffff0000, v204
	v_add_f32_e32 v141, v141, v144
	v_lshlrev_b32_e32 v144, 16, v205
	v_add_f32_e32 v142, v142, v144
	v_and_b32_e32 v144, 0xffff0000, v205
	v_add_f32_e32 v143, v143, v144
	v_lshlrev_b32_e32 v144, 16, v206
	v_add_f32_e32 v144, v136, v144
	v_and_b32_e32 v136, 0xffff0000, v206
	v_add_f32_e32 v145, v137, v136
	v_lshlrev_b32_e32 v136, 16, v207
	v_add_f32_e32 v146, v138, v136
	v_and_b32_e32 v136, 0xffff0000, v207
	v_add_f32_e32 v139, v139, v136
	v_mul_f32_e32 v136, v144, v144
	v_fmac_f32_e32 v136, v140, v140
	v_mul_f32_e32 v137, v145, v145
	v_add_f32_e32 v136, v136, v201
	v_fmac_f32_e32 v137, v141, v141
	v_add_f32_e32 v136, v137, v136
	v_mul_f32_e32 v137, v146, v146
	v_fmac_f32_e32 v137, v142, v142
	v_add_f32_e32 v136, v137, v136
	v_mul_f32_e32 v137, v139, v139
	v_fmac_f32_e32 v137, v143, v143
	v_add_f32_e32 v147, v137, v136
	v_cvt_pk_bf16_f32 v136, v140, v141
	v_cvt_pk_bf16_f32 v137, v142, v143
	v_cvt_pk_bf16_f32 v138, v144, v145
	v_cvt_pk_bf16_f32 v139, v146, v139
	global_store_dwordx4 v[148:149], v[136:139], off offset:256
	s_nop 1
	v_and_b32_e32 v137, 64, v225
	v_xor_b32_e32 v136, 16, v225
	v_add_u32_e32 v137, 64, v137
	v_cmp_lt_i32_e32 vcc, v136, v137
	v_xor_b32_e32 v139, 32, v225
	s_nop 0
	v_cndmask_b32_e32 v136, v225, v136, vcc
	v_lshlrev_b32_e32 v136, 2, v136
	ds_bpermute_b32 v138, v136, v147
	v_cmp_lt_i32_e32 vcc, v139, v137
	s_waitcnt lgkmcnt(0)
	v_add_f32_e32 v138, v147, v138
	v_cndmask_b32_e32 v137, v225, v139, vcc
	v_lshlrev_b32_e32 v137, 2, v137
	ds_bpermute_b32 v139, v137, v138
	s_and_saveexec_b64 s[28:29], s[38:39]
	s_cbranch_execz .LBB0_103
	v_lshlrev_b64 v[140:141], 6, v[166:167]
	v_lshl_add_u64 v[140:141], s[62:63], 0, v[140:141]
	v_lshl_add_u64 v[140:141], s[48:49], 2, v[140:141]
	s_lshl_b32 s34, s9, 2
	v_lshl_add_u64 v[140:141], v[140:141], 0, s[34:35]
	s_waitcnt lgkmcnt(0)
	v_add_f32_e32 v138, v138, v139
	global_store_dword v[140:141], v138, off

.LBB0_147:
	s_add_u32 s21, s0, 0xfffc0080
	s_addc_u32 s28, s1, -1
	s_add_i32 s60, 0, 0x10000
	v_add_u32_e32 v140, s60, v205
	ds_read_b128 v[128:131], v140
	ds_read_b128 v[132:135], v140 offset:1024
	ds_read_b128 v[136:139], v140 offset:2048
	ds_read_b128 v[140:143], v140 offset:3072
	s_cmp_eq_u32 s20, 12
	s_cselect_b32 s49, s43, s28
	s_cselect_b32 s48, s24, s21
	s_cselect_b32 s29, s25, vcc_hi
	s_cselect_b32 s28, s41, vcc_lo
	v_lshl_add_u64 v[174:175], s[0:1], 0, v[150:151]
	s_add_i32 m0, s57, 0xc000
	ds_read_b128 v[154:157], v208
	ds_read_b128 v[158:161], v208 offset:1024
	ds_read_b128 v[162:165], v208 offset:2048
	ds_read_b128 v[166:169], v208 offset:3072
	ds_read_b128 v[170:173], v208 offset:4096
	ds_read_b128 v[198:201], v208 offset:5120
	ds_read_b128 v[210:213], v208 offset:6144
	ds_read_b128 v[214:217], v208 offset:7168
	global_load_lds_dwordx4 v[174:175], off
	v_lshl_add_u64 v[174:175], s[0:1], 0, v[152:153]
	s_add_i32 m0, s57, 0xe000
	s_nop 0
	global_load_lds_dwordx4 v[174:175], off
	s_waitcnt lgkmcnt(8)
	s_barrier
	s_waitcnt lgkmcnt(0)
	s_waitcnt lgkmcnt(0)
	v_mfma_f32_16x16x32_bf16 v[124:127], v[128:131], v[154:157], v[124:127]
	v_mfma_f32_16x16x32_bf16 v[120:123], v[136:139], v[154:157], v[120:123]
	v_mfma_f32_16x16x32_bf16 v[108:111], v[128:131], v[162:165], v[108:111]
	v_mfma_f32_16x16x32_bf16 v[104:107], v[136:139], v[162:165], v[104:107]
	v_mfma_f32_16x16x32_bf16 v[92:95], v[128:131], v[170:173], v[92:95]
	v_mfma_f32_16x16x32_bf16 v[88:91], v[136:139], v[170:173], v[88:91]
	v_mfma_f32_16x16x32_bf16 v[76:79], v[128:131], v[210:213], v[76:79]
	v_mfma_f32_16x16x32_bf16 v[72:75], v[136:139], v[210:213], v[72:75]
	v_mfma_f32_16x16x32_bf16 v[124:127], v[132:135], v[158:161], v[124:127]
	v_mfma_f32_16x16x32_bf16 v[120:123], v[140:143], v[158:161], v[120:123]
	v_mfma_f32_16x16x32_bf16 v[108:111], v[132:135], v[166:169], v[108:111]
	v_mfma_f32_16x16x32_bf16 v[104:107], v[140:143], v[166:169], v[104:107]
	v_mfma_f32_16x16x32_bf16 v[92:95], v[132:135], v[198:201], v[92:95]
	v_mfma_f32_16x16x32_bf16 v[88:91], v[140:143], v[198:201], v[88:91]
	v_mfma_f32_16x16x32_bf16 v[76:79], v[132:135], v[214:217], v[76:79]
	v_mfma_f32_16x16x32_bf16 v[72:75], v[140:143], v[214:217], v[72:75]
	s_barrier
	s_add_i32 s21, 0, 0x14000
	v_add_u32_e32 v174, s21, v205
	s_add_i32 s60, s60, s56
	ds_read_b128 v[232:235], v174
	ds_read_b128 v[236:239], v174 offset:1024
	ds_read_b128 v[240:243], v174 offset:2048
	ds_read_b128 v[244:247], v174 offset:3072
	v_lshl_add_u64 v[174:175], s[28:29], 0, v[176:177]
	s_mov_b32 m0, s60
	v_lshl_add_u64 v[184:185], s[28:29], 0, v[144:145]
	global_load_lds_dwordx4 v[174:175], off
	s_add_i32 m0, s60, 0x2000
	s_nop 0
	global_load_lds_dwordx4 v[184:185], off
	s_barrier
	s_waitcnt lgkmcnt(0)
	s_waitcnt lgkmcnt(0)
	v_mfma_f32_16x16x32_bf16 v[116:119], v[232:235], v[154:157], v[116:119]
	v_mfma_f32_16x16x32_bf16 v[112:115], v[240:243], v[154:157], v[112:115]
	v_mfma_f32_16x16x32_bf16 v[100:103], v[232:235], v[162:165], v[100:103]
	v_mfma_f32_16x16x32_bf16 v[96:99], v[240:243], v[162:165], v[96:99]
	v_mfma_f32_16x16x32_bf16 v[84:87], v[232:235], v[170:173], v[84:87]
	v_mfma_f32_16x16x32_bf16 v[80:83], v[240:243], v[170:173], v[80:83]
	v_mfma_f32_16x16x32_bf16 v[68:71], v[232:235], v[210:213], v[68:71]
	v_mfma_f32_16x16x32_bf16 v[64:67], v[240:243], v[210:213], v[64:67]
	v_mfma_f32_16x16x32_bf16 v[116:119], v[236:239], v[158:161], v[116:119]
	v_mfma_f32_16x16x32_bf16 v[112:115], v[244:247], v[158:161], v[112:115]
	v_mfma_f32_16x16x32_bf16 v[100:103], v[236:239], v[166:169], v[100:103]
	v_mfma_f32_16x16x32_bf16 v[96:99], v[244:247], v[166:169], v[96:99]
	v_mfma_f32_16x16x32_bf16 v[84:87], v[236:239], v[198:201], v[84:87]
	v_mfma_f32_16x16x32_bf16 v[80:83], v[244:247], v[198:201], v[80:83]
	v_mfma_f32_16x16x32_bf16 v[68:71], v[236:239], v[214:217], v[68:71]
	v_mfma_f32_16x16x32_bf16 v[64:67], v[244:247], v[214:217], v[64:67]
	s_mov_b32 m0, s57
	v_lshl_add_u64 v[192:193], s[48:49], 0, v[148:149]
	s_barrier
	ds_read_b128 v[154:157], v208 offset:16384
	ds_read_b128 v[158:161], v208 offset:17408
	ds_read_b128 v[162:165], v208 offset:18432
	ds_read_b128 v[166:169], v208 offset:19456
	ds_read_b128 v[170:173], v208 offset:20480
	ds_read_b128 v[198:201], v208 offset:21504
	ds_read_b128 v[210:213], v208 offset:22528
	ds_read_b128 v[214:217], v208 offset:23552
	global_load_lds_dwordx4 v[192:193], off
	v_lshl_add_u64 v[194:195], s[48:49], 0, v[146:147]
	s_mov_b32 m0, s58
	s_nop 0
	global_load_lds_dwordx4 v[194:195], off
	s_barrier
	s_waitcnt lgkmcnt(0)
	s_waitcnt lgkmcnt(0)
	v_mfma_f32_16x16x32_bf16 v[60:63], v[128:131], v[154:157], v[60:63]
	v_mfma_f32_16x16x32_bf16 v[56:59], v[136:139], v[154:157], v[56:59]
	v_mfma_f32_16x16x32_bf16 v[44:47], v[128:131], v[162:165], v[44:47]
	v_mfma_f32_16x16x32_bf16 v[40:43], v[136:139], v[162:165], v[40:43]
	v_mfma_f32_16x16x32_bf16 v[28:31], v[128:131], v[170:173], v[28:31]
	v_mfma_f32_16x16x32_bf16 v[24:27], v[136:139], v[170:173], v[24:27]
	v_mfma_f32_16x16x32_bf16 v[12:15], v[128:131], v[210:213], v[12:15]
	v_mfma_f32_16x16x32_bf16 v[8:11], v[136:139], v[210:213], v[8:11]
	v_mfma_f32_16x16x32_bf16 v[60:63], v[132:135], v[158:161], v[60:63]
	v_mfma_f32_16x16x32_bf16 v[56:59], v[140:143], v[158:161], v[56:59]
	v_mfma_f32_16x16x32_bf16 v[44:47], v[132:135], v[166:169], v[44:47]
	v_mfma_f32_16x16x32_bf16 v[40:43], v[140:143], v[166:169], v[40:43]
	v_mfma_f32_16x16x32_bf16 v[28:31], v[132:135], v[198:201], v[28:31]
	v_mfma_f32_16x16x32_bf16 v[24:27], v[140:143], v[198:201], v[24:27]
	v_mfma_f32_16x16x32_bf16 v[12:15], v[132:135], v[214:217], v[12:15]
	v_mfma_f32_16x16x32_bf16 v[8:11], v[140:143], v[214:217], v[8:11]
	s_barrier
	s_add_u32 s60, s28, 0x40000
	s_addc_u32 s61, s29, 0
	s_add_i32 s21, s21, s56
	v_lshl_add_u64 v[128:129], s[60:61], 0, v[176:177]
	s_mov_b32 m0, s21
	s_nop 0
	global_load_lds_dwordx4 v[128:129], off
	v_lshl_add_u64 v[128:129], s[60:61], 0, v[144:145]
	s_add_i32 m0, s21, 0x2000
	s_nop 0
	global_load_lds_dwordx4 v[128:129], off
	s_waitcnt vmcnt(6)
	s_barrier
	v_mfma_f32_16x16x32_bf16 v[52:55], v[232:235], v[154:157], v[52:55]
	v_mfma_f32_16x16x32_bf16 v[48:51], v[240:243], v[154:157], v[48:51]
	v_mfma_f32_16x16x32_bf16 v[36:39], v[232:235], v[162:165], v[36:39]
	v_mfma_f32_16x16x32_bf16 v[32:35], v[240:243], v[162:165], v[32:35]
	v_mfma_f32_16x16x32_bf16 v[20:23], v[232:235], v[170:173], v[20:23]
	v_mfma_f32_16x16x32_bf16 v[16:19], v[240:243], v[170:173], v[16:19]
	v_mfma_f32_16x16x32_bf16 v[4:7], v[232:235], v[210:213], v[4:7]
	v_mfma_f32_16x16x32_bf16 v[0:3], v[240:243], v[210:213], v[0:3]
	v_mfma_f32_16x16x32_bf16 v[52:55], v[236:239], v[158:161], v[52:55]
	v_mfma_f32_16x16x32_bf16 v[48:51], v[244:247], v[158:161], v[48:51]
	v_mfma_f32_16x16x32_bf16 v[36:39], v[236:239], v[166:169], v[36:39]
	v_mfma_f32_16x16x32_bf16 v[32:35], v[244:247], v[166:169], v[32:35]
	v_mfma_f32_16x16x32_bf16 v[20:23], v[236:239], v[198:201], v[20:23]
	v_mfma_f32_16x16x32_bf16 v[16:19], v[244:247], v[198:201], v[16:19]
	v_mfma_f32_16x16x32_bf16 v[4:7], v[236:239], v[214:217], v[4:7]
	v_mfma_f32_16x16x32_bf16 v[0:3], v[244:247], v[214:217], v[0:3]
	s_add_i32 s21, 0, 0x18000
	v_add_u32_e32 v140, s21, v205
	s_barrier
	ds_read_b128 v[128:131], v140
	ds_read_b128 v[132:135], v140 offset:1024
	ds_read_b128 v[136:139], v140 offset:2048
	ds_read_b128 v[140:143], v140 offset:3072
	s_add_u32 s48, s48, 0x40000
	s_addc_u32 s49, s49, 0
	s_mov_b32 m0, s7
	v_lshl_add_u64 v[202:203], s[48:49], 0, v[148:149]
	ds_read_b128 v[154:157], v208 offset:32768
	ds_read_b128 v[158:161], v208 offset:33792
	ds_read_b128 v[162:165], v208 offset:34816
	ds_read_b128 v[166:169], v208 offset:35840
	ds_read_b128 v[170:173], v208 offset:36864
	ds_read_b128 v[198:201], v208 offset:37888
	ds_read_b128 v[210:213], v208 offset:38912
	ds_read_b128 v[214:217], v208 offset:39936
	global_load_lds_dwordx4 v[202:203], off
	v_lshl_add_u64 v[202:203], s[48:49], 0, v[146:147]
	s_mov_b32 m0, s15
	s_nop 0
	global_load_lds_dwordx4 v[202:203], off
	s_waitcnt lgkmcnt(8)
	s_barrier
	s_waitcnt lgkmcnt(0)
	s_waitcnt lgkmcnt(0)
	v_mfma_f32_16x16x32_bf16 v[124:127], v[128:131], v[154:157], v[124:127]
	v_mfma_f32_16x16x32_bf16 v[120:123], v[136:139], v[154:157], v[120:123]
	v_mfma_f32_16x16x32_bf16 v[108:111], v[128:131], v[162:165], v[108:111]
	v_mfma_f32_16x16x32_bf16 v[104:107], v[136:139], v[162:165], v[104:107]
	v_mfma_f32_16x16x32_bf16 v[92:95], v[128:131], v[170:173], v[92:95]
	v_mfma_f32_16x16x32_bf16 v[88:91], v[136:139], v[170:173], v[88:91]
	v_mfma_f32_16x16x32_bf16 v[76:79], v[128:131], v[210:213], v[76:79]
	v_mfma_f32_16x16x32_bf16 v[72:75], v[136:139], v[210:213], v[72:75]
	v_mfma_f32_16x16x32_bf16 v[124:127], v[132:135], v[158:161], v[124:127]
	v_mfma_f32_16x16x32_bf16 v[120:123], v[140:143], v[158:161], v[120:123]
	v_mfma_f32_16x16x32_bf16 v[108:111], v[132:135], v[166:169], v[108:111]
	v_mfma_f32_16x16x32_bf16 v[104:107], v[140:143], v[166:169], v[104:107]
	v_mfma_f32_16x16x32_bf16 v[92:95], v[132:135], v[198:201], v[92:95]
	v_mfma_f32_16x16x32_bf16 v[88:91], v[140:143], v[198:201], v[88:91]
	v_mfma_f32_16x16x32_bf16 v[76:79], v[132:135], v[214:217], v[76:79]
	v_mfma_f32_16x16x32_bf16 v[72:75], v[140:143], v[214:217], v[72:75]
	s_barrier
	s_add_i32 s48, 0, 0x1c000
	s_add_i32 s21, s21, s56
	v_add_u32_e32 v202, s48, v205
	v_lshl_add_u64 v[174:175], v[174:175], 0, s[52:53]
	s_mov_b32 m0, s21
	ds_read_b128 v[232:235], v202
	ds_read_b128 v[236:239], v202 offset:1024
	ds_read_b128 v[240:243], v202 offset:2048
	ds_read_b128 v[244:247], v202 offset:3072
	global_load_lds_dwordx4 v[174:175], off
	v_lshl_add_u64 v[174:175], v[184:185], 0, s[52:53]
	s_add_i32 m0, s21, 0x2000
	s_nop 0
	global_load_lds_dwordx4 v[174:175], off
	s_barrier
	s_waitcnt lgkmcnt(0)
	s_waitcnt lgkmcnt(0)
	v_mfma_f32_16x16x32_bf16 v[116:119], v[232:235], v[154:157], v[116:119]
	v_mfma_f32_16x16x32_bf16 v[112:115], v[240:243], v[154:157], v[112:115]
	v_mfma_f32_16x16x32_bf16 v[100:103], v[232:235], v[162:165], v[100:103]
	v_mfma_f32_16x16x32_bf16 v[96:99], v[240:243], v[162:165], v[96:99]
	v_mfma_f32_16x16x32_bf16 v[84:87], v[232:235], v[170:173], v[84:87]
	v_mfma_f32_16x16x32_bf16 v[80:83], v[240:243], v[170:173], v[80:83]
	v_mfma_f32_16x16x32_bf16 v[68:71], v[232:235], v[210:213], v[68:71]
	v_mfma_f32_16x16x32_bf16 v[64:67], v[240:243], v[210:213], v[64:67]
	v_mfma_f32_16x16x32_bf16 v[116:119], v[236:239], v[158:161], v[116:119]
	v_mfma_f32_16x16x32_bf16 v[112:115], v[244:247], v[158:161], v[112:115]
	v_mfma_f32_16x16x32_bf16 v[100:103], v[236:239], v[166:169], v[100:103]
	v_mfma_f32_16x16x32_bf16 v[96:99], v[244:247], v[166:169], v[96:99]
	v_mfma_f32_16x16x32_bf16 v[84:87], v[236:239], v[198:201], v[84:87]
	v_mfma_f32_16x16x32_bf16 v[80:83], v[244:247], v[198:201], v[80:83]
	v_mfma_f32_16x16x32_bf16 v[68:71], v[236:239], v[214:217], v[68:71]
	v_mfma_f32_16x16x32_bf16 v[64:67], v[244:247], v[214:217], v[64:67]
	s_mov_b32 m0, s3
	v_lshl_add_u64 v[174:175], v[192:193], 0, s[52:53]
	s_barrier
	ds_read_b128 v[154:157], v208 offset:49152
	ds_read_b128 v[158:161], v208 offset:50176
	ds_read_b128 v[162:165], v208 offset:51200
	ds_read_b128 v[166:169], v208 offset:52224
	ds_read_b128 v[170:173], v208 offset:53248
	ds_read_b128 v[198:201], v208 offset:54272
	ds_read_b128 v[210:213], v208 offset:55296
	ds_read_b128 v[214:217], v208 offset:56320
	global_load_lds_dwordx4 v[174:175], off
	v_lshl_add_u64 v[174:175], v[194:195], 0, s[52:53]
	s_mov_b32 m0, s6
	s_nop 0
	global_load_lds_dwordx4 v[174:175], off
	s_barrier
	s_waitcnt lgkmcnt(0)
	s_waitcnt lgkmcnt(0)
	v_mfma_f32_16x16x32_bf16 v[60:63], v[128:131], v[154:157], v[60:63]
	v_mfma_f32_16x16x32_bf16 v[56:59], v[136:139], v[154:157], v[56:59]
	v_mfma_f32_16x16x32_bf16 v[44:47], v[128:131], v[162:165], v[44:47]
	v_mfma_f32_16x16x32_bf16 v[40:43], v[136:139], v[162:165], v[40:43]
	v_mfma_f32_16x16x32_bf16 v[28:31], v[128:131], v[170:173], v[28:31]
	v_mfma_f32_16x16x32_bf16 v[24:27], v[136:139], v[170:173], v[24:27]
	v_mfma_f32_16x16x32_bf16 v[12:15], v[128:131], v[210:213], v[12:15]
	v_mfma_f32_16x16x32_bf16 v[8:11], v[136:139], v[210:213], v[8:11]
	v_mfma_f32_16x16x32_bf16 v[60:63], v[132:135], v[158:161], v[60:63]
	v_mfma_f32_16x16x32_bf16 v[56:59], v[140:143], v[158:161], v[56:59]
	v_mfma_f32_16x16x32_bf16 v[44:47], v[132:135], v[166:169], v[44:47]
	v_mfma_f32_16x16x32_bf16 v[40:43], v[140:143], v[166:169], v[40:43]
	v_mfma_f32_16x16x32_bf16 v[28:31], v[132:135], v[198:201], v[28:31]
	v_mfma_f32_16x16x32_bf16 v[24:27], v[140:143], v[198:201], v[24:27]
	v_mfma_f32_16x16x32_bf16 v[12:15], v[132:135], v[214:217], v[12:15]
	v_mfma_f32_16x16x32_bf16 v[8:11], v[140:143], v[214:217], v[8:11]
	s_barrier
	s_add_u32 s28, s28, 0x40080
	s_addc_u32 s29, s29, 0
	s_add_i32 s21, s48, s56
	v_lshl_add_u64 v[128:129], s[28:29], 0, v[176:177]
	s_mov_b32 m0, s21
	s_nop 0
	global_load_lds_dwordx4 v[128:129], off
	v_lshl_add_u64 v[128:129], s[28:29], 0, v[144:145]
	s_add_i32 m0, s21, 0x2000
	s_nop 0
	global_load_lds_dwordx4 v[128:129], off
	s_waitcnt vmcnt(6)
	s_barrier
	v_mfma_f32_16x16x32_bf16 v[52:55], v[232:235], v[154:157], v[52:55]
	v_mfma_f32_16x16x32_bf16 v[48:51], v[240:243], v[154:157], v[48:51]
	v_mfma_f32_16x16x32_bf16 v[36:39], v[232:235], v[162:165], v[36:39]
	v_mfma_f32_16x16x32_bf16 v[32:35], v[240:243], v[162:165], v[32:35]
	v_mfma_f32_16x16x32_bf16 v[20:23], v[232:235], v[170:173], v[20:23]
	v_mfma_f32_16x16x32_bf16 v[16:19], v[240:243], v[170:173], v[16:19]
	v_mfma_f32_16x16x32_bf16 v[4:7], v[232:235], v[210:213], v[4:7]
	v_mfma_f32_16x16x32_bf16 v[0:3], v[240:243], v[210:213], v[0:3]
	v_mfma_f32_16x16x32_bf16 v[52:55], v[236:239], v[158:161], v[52:55]
	v_mfma_f32_16x16x32_bf16 v[48:51], v[244:247], v[158:161], v[48:51]
	v_mfma_f32_16x16x32_bf16 v[36:39], v[236:239], v[166:169], v[36:39]
	v_mfma_f32_16x16x32_bf16 v[32:35], v[244:247], v[166:169], v[32:35]
	v_mfma_f32_16x16x32_bf16 v[20:23], v[236:239], v[198:201], v[20:23]
	v_mfma_f32_16x16x32_bf16 v[16:19], v[244:247], v[198:201], v[16:19]
	v_mfma_f32_16x16x32_bf16 v[4:7], v[236:239], v[214:217], v[4:7]
	v_mfma_f32_16x16x32_bf16 v[0:3], v[244:247], v[214:217], v[0:3]
	s_add_i32 s20, s20, 2
	s_add_u32 s0, s0, 0x100
	s_addc_u32 s1, s1, 0
	s_add_u32 vcc_lo, vcc_lo, 0x100
	s_addc_u32 vcc_hi, vcc_hi, 0
	s_cmp_gt_u32 s20, 13
	s_barrier
	s_cbranch_scc0 .LBB0_147
	s_cmp_eq_u32 s2, s51
	s_cselect_b64 s[48:49], -1, 0
	s_cmp_eq_u32 s2, s50
	v_lshl_add_u32 v170, s2, 8, v204
	s_cselect_b64 s[0:1], -1, 0
	s_or_b64 s[20:21], s[48:49], s[0:1]
	v_or_b32_e32 v166, 16, v170
	v_or_b32_e32 v164, 32, v170
	v_or_b32_e32 v162, 48, v170
	v_add_u32_e32 v160, 0x80, v170
	v_add_u32_e32 v158, 0x90, v170
	v_add_u32_e32 v156, 0xa0, v170
	v_add_u32_e32 v154, 0xb0, v170
	s_mov_b64 s[0:1], -1
	s_and_b64 vcc, exec, s[20:21]
	v_ashrrev_i32_e32 v171, 31, v170
	v_ashrrev_i32_e32 v167, 31, v166
	v_ashrrev_i32_e32 v165, 31, v164
	v_ashrrev_i32_e32 v163, 31, v162
	v_ashrrev_i32_e32 v161, 31, v160
	v_ashrrev_i32_e32 v159, 31, v158
	v_ashrrev_i32_e32 v157, 31, v156
	v_ashrrev_i32_e32 v155, 31, v154
	s_cbranch_vccnz .LBB0_150
	v_readlane_b32 s20, v253, 31
	v_lshlrev_b64 v[128:129], 6, v[170:171]
	v_readlane_b32 s21, v253, 32
	s_mov_b32 s0, 0x3727c5ac
	v_mov_b64_e32 v[198:199], s[0:1]
	v_lshl_add_u64 v[140:141], s[20:21], 0, v[128:129]
	global_load_dwordx4 v[128:131], v[140:141], off offset:32
	global_load_dwordx4 v[132:135], v[140:141], off offset:48
	global_load_dwordx4 v[136:139], v[140:141], off
	s_nop 0
	global_load_dwordx4 v[140:143], v[140:141], off offset:16
	s_mov_b32 s2, 0x3a800000
	s_mov_b32 s24, 0x45800000
	s_waitcnt vmcnt(0)
	v_pk_add_f32 v[128:129], v[128:129], v[132:133]
	v_pk_add_f32 v[130:131], v[130:131], v[134:135]
	v_pk_add_f32 v[136:137], v[136:137], v[140:141]
	v_pk_add_f32 v[138:139], v[138:139], v[142:143]
	v_pk_add_f32 v[172:173], v[136:137], v[128:129]
	v_lshlrev_b64 v[128:129], 6, v[166:167]
	v_lshl_add_u64 v[140:141], s[20:21], 0, v[128:129]
	v_pk_add_f32 v[168:169], v[138:139], v[130:131]
	global_load_dwordx4 v[128:131], v[140:141], off offset:32
	global_load_dwordx4 v[132:135], v[140:141], off offset:48
	global_load_dwordx4 v[136:139], v[140:141], off
	s_nop 0
	global_load_dwordx4 v[140:143], v[140:141], off offset:16
	s_waitcnt vmcnt(0)
	v_pk_add_f32 v[128:129], v[128:129], v[132:133]
	v_pk_add_f32 v[130:131], v[130:131], v[134:135]
	v_pk_add_f32 v[136:137], v[136:137], v[140:141]
	v_pk_add_f32 v[138:139], v[138:139], v[142:143]
	v_pk_add_f32 v[128:129], v[136:137], v[128:129]
	v_pk_add_f32 v[130:131], v[138:139], v[130:131]
	v_mov_b32_e32 v132, v128
	v_mov_b32_e32 v133, v172
	v_mov_b32_e32 v172, v129
	v_pk_add_f32 v[128:129], v[132:133], v[172:173]
	v_mov_b32_e32 v132, v130
	v_mov_b32_e32 v133, v168
	v_pk_add_f32 v[128:129], v[132:133], v[128:129]
	v_mov_b32_e32 v168, v131
	v_pk_add_f32 v[128:129], v[168:169], v[128:129]
	s_nop 0
	v_pk_fma_f32 v[128:129], v[128:129], s[2:3], v[198:199] op_sel_hi:[1,0,0]
	s_nop 0
	v_mul_f32_e32 v130, 0x4b800000, v129
	v_cmp_gt_f32_e64 s[0:1], s23, v129
	v_cmp_gt_f32_e32 vcc, s23, v128
	s_nop 0
	v_cndmask_b32_e64 v129, v129, v130, s[0:1]
	v_mul_f32_e32 v130, 0x4b800000, v128
	v_cndmask_b32_e32 v128, v128, v130, vcc
	v_rsq_f32_e32 v129, v129
	v_rsq_f32_e32 v128, v128
	s_nop 0
	v_pk_mul_f32 v[130:131], v[128:129], s[24:25] op_sel_hi:[1,0]
	s_nop 0
	v_cndmask_b32_e32 v169, v128, v130, vcc
	v_cndmask_b32_e64 v168, v129, v131, s[0:1]
	v_lshlrev_b64 v[128:129], 6, v[164:165]
	v_lshl_add_u64 v[140:141], s[20:21], 0, v[128:129]
	global_load_dwordx4 v[128:131], v[140:141], off offset:32
	global_load_dwordx4 v[132:135], v[140:141], off offset:48
	global_load_dwordx4 v[136:139], v[140:141], off
	s_nop 0
	global_load_dwordx4 v[140:143], v[140:141], off offset:16
	s_waitcnt vmcnt(0)
	v_pk_add_f32 v[128:129], v[128:129], v[132:133]
	v_pk_add_f32 v[130:131], v[130:131], v[134:135]
	v_pk_add_f32 v[136:137], v[136:137], v[140:141]
	v_pk_add_f32 v[138:139], v[138:139], v[142:143]
	v_pk_add_f32 v[174:175], v[136:137], v[128:129]
	v_lshlrev_b64 v[128:129], 6, v[162:163]
	v_lshl_add_u64 v[140:141], s[20:21], 0, v[128:129]
	v_pk_add_f32 v[172:173], v[138:139], v[130:131]
	global_load_dwordx4 v[128:131], v[140:141], off offset:32
	global_load_dwordx4 v[132:135], v[140:141], off offset:48
	global_load_dwordx4 v[136:139], v[140:141], off
	s_nop 0
	global_load_dwordx4 v[140:143], v[140:141], off offset:16
	s_waitcnt vmcnt(0)
	v_pk_add_f32 v[128:129], v[128:129], v[132:133]
	v_pk_add_f32 v[130:131], v[130:131], v[134:135]
	v_pk_add_f32 v[136:137], v[136:137], v[140:141]
	v_pk_add_f32 v[138:139], v[138:139], v[142:143]
	v_pk_add_f32 v[128:129], v[136:137], v[128:129]
	v_pk_add_f32 v[130:131], v[138:139], v[130:131]
	v_mov_b32_e32 v132, v128
	v_mov_b32_e32 v133, v174
	v_mov_b32_e32 v174, v129
	v_pk_add_f32 v[128:129], v[132:133], v[174:175]
	v_mov_b32_e32 v132, v130
	v_mov_b32_e32 v133, v172
	v_pk_add_f32 v[128:129], v[132:133], v[128:129]
	v_mov_b32_e32 v172, v131
	v_pk_add_f32 v[128:129], v[172:173], v[128:129]
	s_nop 0
	v_pk_fma_f32 v[128:129], v[128:129], s[2:3], v[198:199] op_sel_hi:[1,0,0]
	s_nop 0
	v_mul_f32_e32 v130, 0x4b800000, v129
	v_cmp_gt_f32_e64 s[0:1], s23, v129
	v_cmp_gt_f32_e32 vcc, s23, v128
	s_nop 0
	v_cndmask_b32_e64 v129, v129, v130, s[0:1]
	v_mul_f32_e32 v130, 0x4b800000, v128
	v_cndmask_b32_e32 v128, v128, v130, vcc
	v_rsq_f32_e32 v129, v129
	v_rsq_f32_e32 v128, v128
	s_nop 0
	v_pk_mul_f32 v[130:131], v[128:129], s[24:25] op_sel_hi:[1,0]
	s_nop 0
	v_cndmask_b32_e32 v173, v128, v130, vcc
	v_cndmask_b32_e64 v172, v129, v131, s[0:1]
	v_lshlrev_b64 v[128:129], 6, v[160:161]
	v_lshl_add_u64 v[140:141], s[20:21], 0, v[128:129]
	global_load_dwordx4 v[128:131], v[140:141], off offset:32
	global_load_dwordx4 v[132:135], v[140:141], off offset:48
	global_load_dwordx4 v[136:139], v[140:141], off
	s_nop 0
	global_load_dwordx4 v[140:143], v[140:141], off offset:16
	s_waitcnt vmcnt(0)
	v_pk_add_f32 v[128:129], v[128:129], v[132:133]
	v_pk_add_f32 v[130:131], v[130:131], v[134:135]
	v_pk_add_f32 v[136:137], v[136:137], v[140:141]
	v_pk_add_f32 v[138:139], v[138:139], v[142:143]
	v_pk_add_f32 v[184:185], v[136:137], v[128:129]
	v_lshlrev_b64 v[128:129], 6, v[158:159]
	v_lshl_add_u64 v[140:141], s[20:21], 0, v[128:129]
	v_pk_add_f32 v[174:175], v[138:139], v[130:131]
	global_load_dwordx4 v[128:131], v[140:141], off offset:32
	global_load_dwordx4 v[132:135], v[140:141], off offset:48
	global_load_dwordx4 v[136:139], v[140:141], off
	s_nop 0
	global_load_dwordx4 v[140:143], v[140:141], off offset:16
	s_waitcnt vmcnt(0)
	v_pk_add_f32 v[128:129], v[128:129], v[132:133]
	v_pk_add_f32 v[130:131], v[130:131], v[134:135]
	v_pk_add_f32 v[136:137], v[136:137], v[140:141]
	v_pk_add_f32 v[138:139], v[138:139], v[142:143]
	v_pk_add_f32 v[128:129], v[136:137], v[128:129]
	v_pk_add_f32 v[130:131], v[138:139], v[130:131]
	v_mov_b32_e32 v132, v128
	v_mov_b32_e32 v133, v184
	v_mov_b32_e32 v184, v129
	v_pk_add_f32 v[128:129], v[132:133], v[184:185]
	v_mov_b32_e32 v132, v130
	v_mov_b32_e32 v133, v174
	v_pk_add_f32 v[128:129], v[132:133], v[128:129]
	v_mov_b32_e32 v174, v131
	v_pk_add_f32 v[128:129], v[174:175], v[128:129]
	s_nop 0
	v_pk_fma_f32 v[128:129], v[128:129], s[2:3], v[198:199] op_sel_hi:[1,0,0]
	s_nop 0
	v_mul_f32_e32 v130, 0x4b800000, v129
	v_cmp_gt_f32_e64 s[0:1], s23, v129
	v_cmp_gt_f32_e32 vcc, s23, v128
	s_nop 0
	v_cndmask_b32_e64 v129, v129, v130, s[0:1]
	v_mul_f32_e32 v130, 0x4b800000, v128
	v_cndmask_b32_e32 v128, v128, v130, vcc
	v_rsq_f32_e32 v129, v129
	v_rsq_f32_e32 v128, v128
	s_nop 0
	v_pk_mul_f32 v[130:131], v[128:129], s[24:25] op_sel_hi:[1,0]
	s_nop 0
	v_cndmask_b32_e32 v175, v128, v130, vcc
	v_cndmask_b32_e64 v174, v129, v131, s[0:1]
	v_lshlrev_b64 v[128:129], 6, v[156:157]
	v_lshl_add_u64 v[140:141], s[20:21], 0, v[128:129]
	global_load_dwordx4 v[128:131], v[140:141], off offset:32
	global_load_dwordx4 v[132:135], v[140:141], off offset:48
	global_load_dwordx4 v[136:139], v[140:141], off
	s_nop 0
	global_load_dwordx4 v[140:143], v[140:141], off offset:16
	s_waitcnt vmcnt(0)
	v_pk_add_f32 v[128:129], v[128:129], v[132:133]
	v_pk_add_f32 v[130:131], v[130:131], v[134:135]
	v_pk_add_f32 v[136:137], v[136:137], v[140:141]
	v_pk_add_f32 v[138:139], v[138:139], v[142:143]
	v_pk_add_f32 v[202:203], v[136:137], v[128:129]
	v_lshlrev_b64 v[128:129], 6, v[154:155]
	v_lshl_add_u64 v[140:141], s[20:21], 0, v[128:129]
	v_pk_add_f32 v[200:201], v[138:139], v[130:131]
	global_load_dwordx4 v[128:131], v[140:141], off offset:32
	global_load_dwordx4 v[132:135], v[140:141], off offset:48
	global_load_dwordx4 v[136:139], v[140:141], off
	s_nop 0
	global_load_dwordx4 v[140:143], v[140:141], off offset:16
	s_waitcnt vmcnt(0)
	v_pk_add_f32 v[128:129], v[128:129], v[132:133]
	v_pk_add_f32 v[130:131], v[130:131], v[134:135]
	v_pk_add_f32 v[136:137], v[136:137], v[140:141]
	v_pk_add_f32 v[138:139], v[138:139], v[142:143]
	v_pk_add_f32 v[128:129], v[136:137], v[128:129]
	v_pk_add_f32 v[130:131], v[138:139], v[130:131]
	v_mov_b32_e32 v132, v128
	v_mov_b32_e32 v133, v202
	v_mov_b32_e32 v202, v129
	v_pk_add_f32 v[128:129], v[132:133], v[202:203]
	v_mov_b32_e32 v132, v130
	v_mov_b32_e32 v133, v200
	v_pk_add_f32 v[128:129], v[132:133], v[128:129]
	v_mov_b32_e32 v200, v131
	v_pk_add_f32 v[128:129], v[200:201], v[128:129]
	s_nop 0
	v_pk_fma_f32 v[128:129], v[128:129], s[2:3], v[198:199] op_sel_hi:[1,0,0]
	s_nop 0
	v_mul_f32_e32 v130, 0x4b800000, v129
	v_cmp_gt_f32_e64 s[0:1], s23, v129
	v_cmp_gt_f32_e32 vcc, s23, v128
	s_nop 0
	v_cndmask_b32_e64 v129, v129, v130, s[0:1]
	v_rsq_f32_e32 v131, v129
	v_mul_f32_e32 v129, 0x4b800000, v128
	v_cndmask_b32_e32 v128, v128, v129, vcc
	v_rsq_f32_e32 v130, v128
	s_nop 0
	v_pk_mul_f32 v[132:133], v[130:131], s[24:25] op_sel_hi:[1,0]
	s_nop 0
	v_cndmask_b32_e32 v129, v130, v132, vcc
	v_cndmask_b32_e64 v128, v131, v133, s[0:1]
	s_mov_b64 s[0:1], 0

.LBB0_170:
	s_add_u32 s20, s48, 0xfffc0080
	s_addc_u32 s21, s49, -1
	s_add_i32 s60, 0, 0x10000
	v_add_u32_e32 v140, s60, v232
	ds_read_b128 v[128:131], v140
	ds_read_b128 v[132:135], v140 offset:1024
	ds_read_b128 v[136:139], v140 offset:2048
	ds_read_b128 v[140:143], v140 offset:3072
	s_cmp_eq_u32 s57, 12
	s_cselect_b32 s51, s43, s21
	s_cselect_b32 s50, s24, s20
	s_cselect_b32 s29, s1, vcc_hi
	s_cselect_b32 s28, s25, vcc_lo
	v_lshl_add_u64 v[184:185], s[48:49], 0, v[204:205]
	s_add_i32 m0, s55, 0xc000
	ds_read_b128 v[144:147], v234
	ds_read_b128 v[148:151], v234 offset:1024
	ds_read_b128 v[152:155], v234 offset:2048
	ds_read_b128 v[156:159], v234 offset:3072
	ds_read_b128 v[160:163], v234 offset:4096
	ds_read_b128 v[164:167], v234 offset:5120
	ds_read_b128 v[168:171], v234 offset:6144
	ds_read_b128 v[172:175], v234 offset:7168
	global_load_lds_dwordx4 v[184:185], off
	v_lshl_add_u64 v[184:185], s[48:49], 0, v[206:207]
	s_add_i32 m0, s55, 0xe000
	s_nop 0
	global_load_lds_dwordx4 v[184:185], off
	s_waitcnt lgkmcnt(8)
	s_barrier
	s_waitcnt lgkmcnt(0)
	s_waitcnt lgkmcnt(0)
	v_mfma_f32_16x16x32_bf16 v[124:127], v[128:131], v[144:147], v[124:127]
	v_mfma_f32_16x16x32_bf16 v[120:123], v[136:139], v[144:147], v[120:123]
	v_mfma_f32_16x16x32_bf16 v[108:111], v[128:131], v[152:155], v[108:111]
	v_mfma_f32_16x16x32_bf16 v[104:107], v[136:139], v[152:155], v[104:107]
	v_mfma_f32_16x16x32_bf16 v[92:95], v[128:131], v[160:163], v[92:95]
	v_mfma_f32_16x16x32_bf16 v[88:91], v[136:139], v[160:163], v[88:91]
	v_mfma_f32_16x16x32_bf16 v[76:79], v[128:131], v[168:171], v[76:79]
	v_mfma_f32_16x16x32_bf16 v[72:75], v[136:139], v[168:171], v[72:75]
	v_mfma_f32_16x16x32_bf16 v[124:127], v[132:135], v[148:151], v[124:127]
	v_mfma_f32_16x16x32_bf16 v[120:123], v[140:143], v[148:151], v[120:123]
	v_mfma_f32_16x16x32_bf16 v[108:111], v[132:135], v[156:159], v[108:111]
	v_mfma_f32_16x16x32_bf16 v[104:107], v[140:143], v[156:159], v[104:107]
	v_mfma_f32_16x16x32_bf16 v[92:95], v[132:135], v[164:167], v[92:95]
	v_mfma_f32_16x16x32_bf16 v[88:91], v[140:143], v[164:167], v[88:91]
	v_mfma_f32_16x16x32_bf16 v[76:79], v[132:135], v[172:175], v[76:79]
	v_mfma_f32_16x16x32_bf16 v[72:75], v[140:143], v[172:175], v[72:75]
	s_barrier
	s_add_i32 s61, 0, 0x14000
	v_add_u32_e32 v184, s61, v232
	s_add_i32 s20, s60, s54
	ds_read_b128 v[208:211], v184
	ds_read_b128 v[212:215], v184 offset:1024
	ds_read_b128 v[216:219], v184 offset:2048
	ds_read_b128 v[236:239], v184 offset:3072
	v_lshl_add_u64 v[184:185], s[28:29], 0, v[176:177]
	s_mov_b32 m0, s20
	v_lshl_add_u64 v[192:193], s[28:29], 0, v[198:199]
	global_load_lds_dwordx4 v[184:185], off
	s_add_i32 m0, s20, 0x2000
	s_nop 0
	global_load_lds_dwordx4 v[192:193], off
	s_barrier
	s_waitcnt lgkmcnt(0)
	s_waitcnt lgkmcnt(0)
	v_mfma_f32_16x16x32_bf16 v[116:119], v[208:211], v[144:147], v[116:119]
	v_mfma_f32_16x16x32_bf16 v[112:115], v[216:219], v[144:147], v[112:115]
	v_mfma_f32_16x16x32_bf16 v[100:103], v[208:211], v[152:155], v[100:103]
	v_mfma_f32_16x16x32_bf16 v[96:99], v[216:219], v[152:155], v[96:99]
	v_mfma_f32_16x16x32_bf16 v[84:87], v[208:211], v[160:163], v[84:87]
	v_mfma_f32_16x16x32_bf16 v[80:83], v[216:219], v[160:163], v[80:83]
	v_mfma_f32_16x16x32_bf16 v[68:71], v[208:211], v[168:171], v[68:71]
	v_mfma_f32_16x16x32_bf16 v[64:67], v[216:219], v[168:171], v[64:67]
	v_mfma_f32_16x16x32_bf16 v[116:119], v[212:215], v[148:151], v[116:119]
	v_mfma_f32_16x16x32_bf16 v[112:115], v[236:239], v[148:151], v[112:115]
	v_mfma_f32_16x16x32_bf16 v[100:103], v[212:215], v[156:159], v[100:103]
	v_mfma_f32_16x16x32_bf16 v[96:99], v[236:239], v[156:159], v[96:99]
	v_mfma_f32_16x16x32_bf16 v[84:87], v[212:215], v[164:167], v[84:87]
	v_mfma_f32_16x16x32_bf16 v[80:83], v[236:239], v[164:167], v[80:83]
	v_mfma_f32_16x16x32_bf16 v[68:71], v[212:215], v[172:175], v[68:71]
	v_mfma_f32_16x16x32_bf16 v[64:67], v[236:239], v[172:175], v[64:67]
	s_mov_b32 m0, s55
	v_lshl_add_u64 v[194:195], s[50:51], 0, v[202:203]
	s_barrier
	ds_read_b128 v[144:147], v234 offset:16384
	ds_read_b128 v[148:151], v234 offset:17408
	ds_read_b128 v[152:155], v234 offset:18432
	ds_read_b128 v[156:159], v234 offset:19456
	ds_read_b128 v[160:163], v234 offset:20480
	ds_read_b128 v[164:167], v234 offset:21504
	ds_read_b128 v[168:171], v234 offset:22528
	ds_read_b128 v[172:175], v234 offset:23552
	global_load_lds_dwordx4 v[194:195], off
	v_lshl_add_u64 v[240:241], s[50:51], 0, v[200:201]
	s_mov_b32 m0, s56
	s_nop 0
	global_load_lds_dwordx4 v[240:241], off
	s_barrier
	s_waitcnt lgkmcnt(0)
	s_waitcnt lgkmcnt(0)
	v_mfma_f32_16x16x32_bf16 v[60:63], v[128:131], v[144:147], v[60:63]
	v_mfma_f32_16x16x32_bf16 v[56:59], v[136:139], v[144:147], v[56:59]
	v_mfma_f32_16x16x32_bf16 v[44:47], v[128:131], v[152:155], v[44:47]
	v_mfma_f32_16x16x32_bf16 v[40:43], v[136:139], v[152:155], v[40:43]
	v_mfma_f32_16x16x32_bf16 v[28:31], v[128:131], v[160:163], v[28:31]
	v_mfma_f32_16x16x32_bf16 v[24:27], v[136:139], v[160:163], v[24:27]
	v_mfma_f32_16x16x32_bf16 v[12:15], v[128:131], v[168:171], v[12:15]
	v_mfma_f32_16x16x32_bf16 v[8:11], v[136:139], v[168:171], v[8:11]
	v_mfma_f32_16x16x32_bf16 v[60:63], v[132:135], v[148:151], v[60:63]
	v_mfma_f32_16x16x32_bf16 v[56:59], v[140:143], v[148:151], v[56:59]
	v_mfma_f32_16x16x32_bf16 v[44:47], v[132:135], v[156:159], v[44:47]
	v_mfma_f32_16x16x32_bf16 v[40:43], v[140:143], v[156:159], v[40:43]
	v_mfma_f32_16x16x32_bf16 v[28:31], v[132:135], v[164:167], v[28:31]
	v_mfma_f32_16x16x32_bf16 v[24:27], v[140:143], v[164:167], v[24:27]
	v_mfma_f32_16x16x32_bf16 v[12:15], v[132:135], v[172:175], v[12:15]
	v_mfma_f32_16x16x32_bf16 v[8:11], v[140:143], v[172:175], v[8:11]
	s_barrier
	s_add_u32 s20, s28, 0x40000
	s_addc_u32 s21, s29, 0
	s_add_i32 s60, s61, s54
	v_lshl_add_u64 v[128:129], s[20:21], 0, v[176:177]
	s_mov_b32 m0, s60
	s_nop 0
	global_load_lds_dwordx4 v[128:129], off
	v_lshl_add_u64 v[128:129], s[20:21], 0, v[198:199]
	s_add_i32 m0, s60, 0x2000
	s_nop 0
	global_load_lds_dwordx4 v[128:129], off
	s_waitcnt vmcnt(6)
	s_barrier
	v_mfma_f32_16x16x32_bf16 v[52:55], v[208:211], v[144:147], v[52:55]
	v_mfma_f32_16x16x32_bf16 v[48:51], v[216:219], v[144:147], v[48:51]
	v_mfma_f32_16x16x32_bf16 v[36:39], v[208:211], v[152:155], v[36:39]
	v_mfma_f32_16x16x32_bf16 v[32:35], v[216:219], v[152:155], v[32:35]
	v_mfma_f32_16x16x32_bf16 v[20:23], v[208:211], v[160:163], v[20:23]
	v_mfma_f32_16x16x32_bf16 v[16:19], v[216:219], v[160:163], v[16:19]
	v_mfma_f32_16x16x32_bf16 v[4:7], v[208:211], v[168:171], v[4:7]
	v_mfma_f32_16x16x32_bf16 v[0:3], v[216:219], v[168:171], v[0:3]
	v_mfma_f32_16x16x32_bf16 v[52:55], v[212:215], v[148:151], v[52:55]
	v_mfma_f32_16x16x32_bf16 v[48:51], v[236:239], v[148:151], v[48:51]
	v_mfma_f32_16x16x32_bf16 v[36:39], v[212:215], v[156:159], v[36:39]
	v_mfma_f32_16x16x32_bf16 v[32:35], v[236:239], v[156:159], v[32:35]
	v_mfma_f32_16x16x32_bf16 v[20:23], v[212:215], v[164:167], v[20:23]
	v_mfma_f32_16x16x32_bf16 v[16:19], v[236:239], v[164:167], v[16:19]
	v_mfma_f32_16x16x32_bf16 v[4:7], v[212:215], v[172:175], v[4:7]
	v_mfma_f32_16x16x32_bf16 v[0:3], v[236:239], v[172:175], v[0:3]
	s_add_i32 s60, 0, 0x18000
	v_add_u32_e32 v140, s60, v232
	s_barrier
	ds_read_b128 v[128:131], v140
	ds_read_b128 v[132:135], v140 offset:1024
	ds_read_b128 v[136:139], v140 offset:2048
	ds_read_b128 v[140:143], v140 offset:3072
	s_add_u32 s20, s50, 0x40000
	s_addc_u32 s21, s51, 0
	s_mov_b32 m0, s7
	v_lshl_add_u64 v[208:209], s[20:21], 0, v[202:203]
	ds_read_b128 v[144:147], v234 offset:32768
	ds_read_b128 v[148:151], v234 offset:33792
	ds_read_b128 v[152:155], v234 offset:34816
	ds_read_b128 v[156:159], v234 offset:35840
	ds_read_b128 v[160:163], v234 offset:36864
	ds_read_b128 v[164:167], v234 offset:37888
	ds_read_b128 v[168:171], v234 offset:38912
	ds_read_b128 v[172:175], v234 offset:39936
	global_load_lds_dwordx4 v[208:209], off
	v_lshl_add_u64 v[208:209], s[20:21], 0, v[200:201]
	s_mov_b32 m0, s15
	s_nop 0
	global_load_lds_dwordx4 v[208:209], off
	s_waitcnt lgkmcnt(8)
	s_barrier
	s_waitcnt lgkmcnt(0)
	s_waitcnt lgkmcnt(0)
	v_mfma_f32_16x16x32_bf16 v[124:127], v[128:131], v[144:147], v[124:127]
	v_mfma_f32_16x16x32_bf16 v[120:123], v[136:139], v[144:147], v[120:123]
	v_mfma_f32_16x16x32_bf16 v[108:111], v[128:131], v[152:155], v[108:111]
	v_mfma_f32_16x16x32_bf16 v[104:107], v[136:139], v[152:155], v[104:107]
	v_mfma_f32_16x16x32_bf16 v[92:95], v[128:131], v[160:163], v[92:95]
	v_mfma_f32_16x16x32_bf16 v[88:91], v[136:139], v[160:163], v[88:91]
	v_mfma_f32_16x16x32_bf16 v[76:79], v[128:131], v[168:171], v[76:79]
	v_mfma_f32_16x16x32_bf16 v[72:75], v[136:139], v[168:171], v[72:75]
	v_mfma_f32_16x16x32_bf16 v[124:127], v[132:135], v[148:151], v[124:127]
	v_mfma_f32_16x16x32_bf16 v[120:123], v[140:143], v[148:151], v[120:123]
	v_mfma_f32_16x16x32_bf16 v[108:111], v[132:135], v[156:159], v[108:111]
	v_mfma_f32_16x16x32_bf16 v[104:107], v[140:143], v[156:159], v[104:107]
	v_mfma_f32_16x16x32_bf16 v[92:95], v[132:135], v[164:167], v[92:95]
	v_mfma_f32_16x16x32_bf16 v[88:91], v[140:143], v[164:167], v[88:91]
	v_mfma_f32_16x16x32_bf16 v[76:79], v[132:135], v[172:175], v[76:79]
	v_mfma_f32_16x16x32_bf16 v[72:75], v[140:143], v[172:175], v[72:75]
	s_barrier
	s_add_i32 s50, 0, 0x1c000
	s_add_i32 s20, s60, s54
	v_add_u32_e32 v235, s50, v232
	v_lshl_add_u64 v[184:185], v[184:185], 0, s[52:53]
	s_mov_b32 m0, s20
	ds_read_b128 v[208:211], v235
	ds_read_b128 v[212:215], v235 offset:1024
	ds_read_b128 v[216:219], v235 offset:2048
	ds_read_b128 v[236:239], v235 offset:3072
	global_load_lds_dwordx4 v[184:185], off
	v_lshl_add_u64 v[184:185], v[192:193], 0, s[52:53]
	s_add_i32 m0, s20, 0x2000
	s_nop 0
	global_load_lds_dwordx4 v[184:185], off
	s_barrier
	s_waitcnt lgkmcnt(0)
	s_waitcnt lgkmcnt(0)
	v_mfma_f32_16x16x32_bf16 v[116:119], v[208:211], v[144:147], v[116:119]
	v_mfma_f32_16x16x32_bf16 v[112:115], v[216:219], v[144:147], v[112:115]
	v_mfma_f32_16x16x32_bf16 v[100:103], v[208:211], v[152:155], v[100:103]
	v_mfma_f32_16x16x32_bf16 v[96:99], v[216:219], v[152:155], v[96:99]
	v_mfma_f32_16x16x32_bf16 v[84:87], v[208:211], v[160:163], v[84:87]
	v_mfma_f32_16x16x32_bf16 v[80:83], v[216:219], v[160:163], v[80:83]
	v_mfma_f32_16x16x32_bf16 v[68:71], v[208:211], v[168:171], v[68:71]
	v_mfma_f32_16x16x32_bf16 v[64:67], v[216:219], v[168:171], v[64:67]
	v_mfma_f32_16x16x32_bf16 v[116:119], v[212:215], v[148:151], v[116:119]
	v_mfma_f32_16x16x32_bf16 v[112:115], v[236:239], v[148:151], v[112:115]
	v_mfma_f32_16x16x32_bf16 v[100:103], v[212:215], v[156:159], v[100:103]
	v_mfma_f32_16x16x32_bf16 v[96:99], v[236:239], v[156:159], v[96:99]
	v_mfma_f32_16x16x32_bf16 v[84:87], v[212:215], v[164:167], v[84:87]
	v_mfma_f32_16x16x32_bf16 v[80:83], v[236:239], v[164:167], v[80:83]
	v_mfma_f32_16x16x32_bf16 v[68:71], v[212:215], v[172:175], v[68:71]
	v_mfma_f32_16x16x32_bf16 v[64:67], v[236:239], v[172:175], v[64:67]
	s_mov_b32 m0, s3
	v_lshl_add_u64 v[184:185], v[194:195], 0, s[52:53]
	s_barrier
	ds_read_b128 v[144:147], v234 offset:49152
	ds_read_b128 v[148:151], v234 offset:50176
	ds_read_b128 v[152:155], v234 offset:51200
	ds_read_b128 v[156:159], v234 offset:52224
	ds_read_b128 v[160:163], v234 offset:53248
	ds_read_b128 v[164:167], v234 offset:54272
	ds_read_b128 v[168:171], v234 offset:55296
	ds_read_b128 v[172:175], v234 offset:56320
	global_load_lds_dwordx4 v[184:185], off
	v_lshl_add_u64 v[184:185], v[240:241], 0, s[52:53]
	s_mov_b32 m0, s6
	s_nop 0
	global_load_lds_dwordx4 v[184:185], off
	s_barrier
	s_waitcnt lgkmcnt(0)
	s_waitcnt lgkmcnt(0)
	v_mfma_f32_16x16x32_bf16 v[60:63], v[128:131], v[144:147], v[60:63]
	v_mfma_f32_16x16x32_bf16 v[56:59], v[136:139], v[144:147], v[56:59]
	v_mfma_f32_16x16x32_bf16 v[44:47], v[128:131], v[152:155], v[44:47]
	v_mfma_f32_16x16x32_bf16 v[40:43], v[136:139], v[152:155], v[40:43]
	v_mfma_f32_16x16x32_bf16 v[28:31], v[128:131], v[160:163], v[28:31]
	v_mfma_f32_16x16x32_bf16 v[24:27], v[136:139], v[160:163], v[24:27]
	v_mfma_f32_16x16x32_bf16 v[12:15], v[128:131], v[168:171], v[12:15]
	v_mfma_f32_16x16x32_bf16 v[8:11], v[136:139], v[168:171], v[8:11]
	v_mfma_f32_16x16x32_bf16 v[60:63], v[132:135], v[148:151], v[60:63]
	v_mfma_f32_16x16x32_bf16 v[56:59], v[140:143], v[148:151], v[56:59]
	v_mfma_f32_16x16x32_bf16 v[44:47], v[132:135], v[156:159], v[44:47]
	v_mfma_f32_16x16x32_bf16 v[40:43], v[140:143], v[156:159], v[40:43]
	v_mfma_f32_16x16x32_bf16 v[28:31], v[132:135], v[164:167], v[28:31]
	v_mfma_f32_16x16x32_bf16 v[24:27], v[140:143], v[164:167], v[24:27]
	v_mfma_f32_16x16x32_bf16 v[12:15], v[132:135], v[172:175], v[12:15]
	v_mfma_f32_16x16x32_bf16 v[8:11], v[140:143], v[172:175], v[8:11]
	s_barrier
	s_add_u32 s20, s28, 0x40080
	s_addc_u32 s21, s29, 0
	s_add_i32 s28, s50, s54
	v_lshl_add_u64 v[128:129], s[20:21], 0, v[176:177]
	s_mov_b32 m0, s28
	s_nop 0
	global_load_lds_dwordx4 v[128:129], off
	v_lshl_add_u64 v[128:129], s[20:21], 0, v[198:199]
	s_add_i32 m0, s28, 0x2000
	s_nop 0
	global_load_lds_dwordx4 v[128:129], off
	s_waitcnt vmcnt(6)
	s_barrier
	v_mfma_f32_16x16x32_bf16 v[52:55], v[208:211], v[144:147], v[52:55]
	v_mfma_f32_16x16x32_bf16 v[48:51], v[216:219], v[144:147], v[48:51]
	v_mfma_f32_16x16x32_bf16 v[36:39], v[208:211], v[152:155], v[36:39]
	v_mfma_f32_16x16x32_bf16 v[32:35], v[216:219], v[152:155], v[32:35]
	v_mfma_f32_16x16x32_bf16 v[20:23], v[208:211], v[160:163], v[20:23]
	v_mfma_f32_16x16x32_bf16 v[16:19], v[216:219], v[160:163], v[16:19]
	v_mfma_f32_16x16x32_bf16 v[4:7], v[208:211], v[168:171], v[4:7]
	v_mfma_f32_16x16x32_bf16 v[0:3], v[216:219], v[168:171], v[0:3]
	v_mfma_f32_16x16x32_bf16 v[52:55], v[212:215], v[148:151], v[52:55]
	v_mfma_f32_16x16x32_bf16 v[48:51], v[236:239], v[148:151], v[48:51]
	v_mfma_f32_16x16x32_bf16 v[36:39], v[212:215], v[156:159], v[36:39]
	v_mfma_f32_16x16x32_bf16 v[32:35], v[236:239], v[156:159], v[32:35]
	v_mfma_f32_16x16x32_bf16 v[20:23], v[212:215], v[164:167], v[20:23]
	v_mfma_f32_16x16x32_bf16 v[16:19], v[236:239], v[164:167], v[16:19]
	v_mfma_f32_16x16x32_bf16 v[4:7], v[212:215], v[172:175], v[4:7]
	v_mfma_f32_16x16x32_bf16 v[0:3], v[236:239], v[172:175], v[0:3]
	s_add_i32 s57, s57, 2
	s_add_u32 s48, s48, 0x100
	s_addc_u32 s49, s49, 0
	s_add_u32 vcc_lo, vcc_lo, 0x100
	s_addc_u32 vcc_hi, vcc_hi, 0
	s_cmp_gt_u32 s57, 13
	s_barrier
	s_cbranch_scc0 .LBB0_170
	v_lshl_add_u32 v210, s2, 8, v231
	v_lshl_or_b32 v208, s34, 8, v233
	v_readlane_b32 s60, v252, 10
	v_ashrrev_i32_e32 v209, 31, v208
	v_readlane_b32 s61, v252, 11
	v_ashrrev_i32_e32 v211, 31, v210
	v_lshlrev_b64 v[128:129], 12, v[210:211]
	v_lshl_add_u64 v[212:213], v[208:209], 2, s[60:61]
	v_lshl_add_u64 v[128:129], v[212:213], 0, v[128:129]
	global_load_dwordx4 v[236:239], v[128:129], off offset:16
	global_load_dwordx4 v[240:243], v[128:129], off
	global_load_dwordx4 v[244:247], v[128:129], off offset:528
	global_load_dwordx4 v[248:251], v[128:129], off offset:512
	v_or_b32_e32 v218, 16, v210
	v_ashrrev_i32_e32 v219, 31, v218
	v_lshlrev_b64 v[128:129], 12, v[218:219]
	v_or_b32_e32 v216, 32, v210
	v_lshl_add_u64 v[128:129], v[212:213], 0, v[128:129]
	v_ashrrev_i32_e32 v217, 31, v216
	global_load_dwordx4 v[168:171], v[128:129], off offset:16
	global_load_dwordx4 v[172:175], v[128:129], off
	global_load_dwordx4 v[160:163], v[128:129], off offset:528
	global_load_dwordx4 v[164:167], v[128:129], off offset:512
	v_lshlrev_b64 v[128:129], 12, v[216:217]
	v_or_b32_e32 v214, 48, v210
	v_lshl_add_u64 v[128:129], v[212:213], 0, v[128:129]
	v_ashrrev_i32_e32 v215, 31, v214
	global_load_dwordx4 v[152:155], v[128:129], off offset:16
	global_load_dwordx4 v[156:159], v[128:129], off
	global_load_dwordx4 v[136:139], v[128:129], off offset:528
	global_load_dwordx4 v[144:147], v[128:129], off offset:512
	v_lshlrev_b64 v[128:129], 12, v[214:215]
	v_lshl_add_u64 v[132:133], v[212:213], 0, v[128:129]
	global_load_dwordx4 v[140:143], v[132:133], off offset:16
	global_load_dwordx4 v[148:151], v[132:133], off
	global_load_dwordx4 v[128:131], v[132:133], off offset:528
	s_nop 0
	global_load_dwordx4 v[132:135], v[132:133], off offset:512
	v_readlane_b32 s68, v252, 18
	v_readlane_b32 s69, v252, 19
	v_readlane_b32 s68, v255, 14
	v_readlane_b32 s69, v255, 15
	s_lshl_b32 s48, s34, 2
	s_ashr_i32 s49, s48, 31
	v_readlane_b32 s62, v252, 12
	v_readlane_b32 s63, v252, 13
	v_readlane_b32 s64, v252, 14
	v_readlane_b32 s65, v252, 15
	v_readlane_b32 s66, v252, 16
	v_readlane_b32 s67, v252, 17
	v_readlane_b32 s70, v252, 20
	v_readlane_b32 s71, v252, 21
	v_readlane_b32 s72, v252, 22
	v_readlane_b32 s73, v252, 23
	v_readlane_b32 s74, v252, 24
	v_readlane_b32 s75, v252, 25
	s_waitcnt vmcnt(0)
	v_pk_add_f32 v[184:185], v[122:123], v[238:239]
	v_pk_add_f32 v[122:123], v[120:121], v[236:237]
	v_pk_add_f32 v[124:125], v[124:125], v[240:241]
	v_mul_f32_e32 v120, v122, v122
	v_mul_f32_e32 v121, v123, v123
	v_fmac_f32_e32 v120, v124, v124
	v_fmac_f32_e32 v121, v125, v125
	v_pk_add_f32 v[126:127], v[126:127], v[242:243]
	v_add_f32_e32 v120, v120, v121
	v_mul_f32_e32 v121, v184, v184
	v_fmac_f32_e32 v121, v126, v126
	v_add_f32_e32 v120, v121, v120
	v_mul_f32_e32 v121, v185, v185
	v_fmac_f32_e32 v121, v127, v127
	v_add_f32_e32 v192, v121, v120
	v_cvt_pk_bf16_f32 v120, v124, v125
	v_lshlrev_b64 v[124:125], 11, v[210:211]
	v_lshl_add_u64 v[124:125], s[68:69], 0, v[124:125]
	v_cvt_pk_bf16_f32 v121, v126, v127
	v_lshl_add_u64 v[124:125], v[208:209], 1, v[124:125]
	v_cvt_pk_bf16_f32 v122, v122, v123
	v_cvt_pk_bf16_f32 v123, v184, v185
	global_store_dwordx4 v[124:125], v[120:123], off
	v_pk_add_f32 v[116:117], v[116:117], v[248:249]
	v_pk_add_f32 v[118:119], v[118:119], v[250:251]
	v_pk_add_f32 v[120:121], v[114:115], v[246:247]
	v_pk_add_f32 v[114:115], v[112:113], v[244:245]
	s_nop 0
	v_mul_f32_e32 v112, v114, v114
	v_fmac_f32_e32 v112, v116, v116
	v_mul_f32_e32 v113, v115, v115
	v_add_f32_e32 v112, v112, v192
	v_fmac_f32_e32 v113, v117, v117
	v_add_f32_e32 v112, v113, v112
	v_mul_f32_e32 v113, v120, v120
	v_fmac_f32_e32 v113, v118, v118
	v_add_f32_e32 v112, v113, v112
	v_mul_f32_e32 v113, v121, v121
	v_fmac_f32_e32 v113, v119, v119
	v_add_f32_e32 v122, v113, v112
	v_cvt_pk_bf16_f32 v112, v116, v117
	v_cvt_pk_bf16_f32 v113, v118, v119
	v_cvt_pk_bf16_f32 v114, v114, v115
	v_cvt_pk_bf16_f32 v115, v120, v121
	global_store_dwordx4 v[124:125], v[112:115], off offset:256
	s_nop 1
	v_and_b32_e32 v113, 64, v225
	v_xor_b32_e32 v112, 16, v225
	v_add_u32_e32 v113, 64, v113
	v_cmp_lt_i32_e32 vcc, v112, v113
	v_xor_b32_e32 v114, 32, v225
	s_nop 0
	v_cndmask_b32_e32 v112, v225, v112, vcc
	v_lshlrev_b32_e32 v235, 2, v112
	ds_bpermute_b32 v112, v235, v122
	v_cmp_lt_i32_e32 vcc, v114, v113
	s_waitcnt lgkmcnt(0)
	v_add_f32_e32 v112, v122, v112
	v_cndmask_b32_e32 v113, v225, v114, vcc
	v_lshlrev_b32_e32 v236, 2, v113
	ds_bpermute_b32 v113, v236, v112
	s_and_saveexec_b64 s[28:29], s[38:39]
	s_cbranch_execz .LBB0_173
	v_readlane_b32 s20, v253, 31
	v_lshlrev_b64 v[114:115], 6, v[210:211]
	v_readlane_b32 s21, v253, 32
	s_lshl_b32 s34, s58, 2
	s_waitcnt lgkmcnt(0)
	v_add_f32_e32 v112, v112, v113
	v_lshl_add_u64 v[114:115], s[20:21], 0, v[114:115]
	v_lshl_add_u64 v[114:115], s[48:49], 2, v[114:115]
	v_lshl_add_u64 v[114:115], v[114:115], 0, s[34:35]
	global_store_dword v[114:115], v112, off

.LBB0_292:
	s_add_u32 s20, s46, 0xfffc0080
	s_addc_u32 s21, s47, -1
	s_add_i32 s60, 0, 0x10000
	v_add_u32_e32 v138, s60, v141
	ds_read_b128 v[144:147], v138
	ds_read_b128 v[148:151], v138 offset:1024
	ds_read_b128 v[152:155], v138 offset:2048
	ds_read_b128 v[156:159], v138 offset:3072
	s_cmp_eq_u32 vcc_lo, 12
	s_cselect_b32 s49, s41, s21
	s_cselect_b32 s48, s24, s20
	s_cselect_b32 s29, s1, s59
	s_cselect_b32 s28, s25, s58
	v_lshl_add_u64 v[138:139], s[46:47], 0, v[134:135]
	s_add_i32 m0, s7, 0xc000
	ds_read_b128 v[160:163], v143
	ds_read_b128 v[164:167], v143 offset:1024
	ds_read_b128 v[168:171], v143 offset:2048
	ds_read_b128 v[172:175], v143 offset:3072
	ds_read_b128 v[198:201], v143 offset:4096
	ds_read_b128 v[202:205], v143 offset:5120
	ds_read_b128 v[206:209], v143 offset:6144
	ds_read_b128 v[210:213], v143 offset:7168
	global_load_lds_dwordx4 v[138:139], off
	v_lshl_add_u64 v[138:139], s[46:47], 0, v[136:137]
	s_add_i32 m0, s7, 0xe000
	s_nop 0
	global_load_lds_dwordx4 v[138:139], off
	s_waitcnt lgkmcnt(8)
	s_barrier
	s_waitcnt lgkmcnt(0)
	s_waitcnt lgkmcnt(0)
	v_mfma_f32_16x16x32_bf16 v[124:127], v[144:147], v[160:163], v[124:127]
	v_mfma_f32_16x16x32_bf16 v[120:123], v[152:155], v[160:163], v[120:123]
	v_mfma_f32_16x16x32_bf16 v[116:119], v[144:147], v[168:171], v[116:119]
	v_mfma_f32_16x16x32_bf16 v[108:111], v[152:155], v[168:171], v[108:111]
	v_mfma_f32_16x16x32_bf16 v[100:103], v[144:147], v[198:201], v[100:103]
	v_mfma_f32_16x16x32_bf16 v[92:95], v[152:155], v[198:201], v[92:95]
	v_mfma_f32_16x16x32_bf16 v[80:83], v[144:147], v[206:209], v[80:83]
	v_mfma_f32_16x16x32_bf16 v[72:75], v[152:155], v[206:209], v[72:75]
	v_mfma_f32_16x16x32_bf16 v[124:127], v[148:151], v[164:167], v[124:127]
	v_mfma_f32_16x16x32_bf16 v[120:123], v[156:159], v[164:167], v[120:123]
	v_mfma_f32_16x16x32_bf16 v[116:119], v[148:151], v[172:175], v[116:119]
	v_mfma_f32_16x16x32_bf16 v[108:111], v[156:159], v[172:175], v[108:111]
	v_mfma_f32_16x16x32_bf16 v[100:103], v[148:151], v[202:205], v[100:103]
	v_mfma_f32_16x16x32_bf16 v[92:95], v[156:159], v[202:205], v[92:95]
	v_mfma_f32_16x16x32_bf16 v[80:83], v[148:151], v[210:213], v[80:83]
	v_mfma_f32_16x16x32_bf16 v[72:75], v[156:159], v[210:213], v[72:75]
	s_barrier
	s_add_i32 s61, 0, 0x14000
	v_add_u32_e32 v138, s61, v141
	s_add_i32 s20, s60, s6
	ds_read_b128 v[214:217], v138
	ds_read_b128 v[232:235], v138 offset:1024
	ds_read_b128 v[236:239], v138 offset:2048
	ds_read_b128 v[240:243], v138 offset:3072
	v_lshl_add_u64 v[138:139], s[28:29], 0, v[176:177]
	s_mov_b32 m0, s20
	v_lshl_add_u64 v[218:219], s[28:29], 0, v[128:129]
	global_load_lds_dwordx4 v[138:139], off
	s_add_i32 m0, s20, 0x2000
	s_nop 0
	global_load_lds_dwordx4 v[218:219], off
	s_barrier
	s_waitcnt lgkmcnt(0)
	s_waitcnt lgkmcnt(0)
	v_mfma_f32_16x16x32_bf16 v[112:115], v[214:217], v[160:163], v[112:115]
	v_mfma_f32_16x16x32_bf16 v[104:107], v[236:239], v[160:163], v[104:107]
	v_mfma_f32_16x16x32_bf16 v[96:99], v[214:217], v[168:171], v[96:99]
	v_mfma_f32_16x16x32_bf16 v[88:91], v[236:239], v[168:171], v[88:91]
	v_mfma_f32_16x16x32_bf16 v[84:87], v[214:217], v[198:201], v[84:87]
	v_mfma_f32_16x16x32_bf16 v[76:79], v[236:239], v[198:201], v[76:79]
	v_mfma_f32_16x16x32_bf16 v[68:71], v[214:217], v[206:209], v[68:71]
	v_mfma_f32_16x16x32_bf16 v[64:67], v[236:239], v[206:209], v[64:67]
	v_mfma_f32_16x16x32_bf16 v[112:115], v[232:235], v[164:167], v[112:115]
	v_mfma_f32_16x16x32_bf16 v[104:107], v[240:243], v[164:167], v[104:107]
	v_mfma_f32_16x16x32_bf16 v[96:99], v[232:235], v[172:175], v[96:99]
	v_mfma_f32_16x16x32_bf16 v[88:91], v[240:243], v[172:175], v[88:91]
	v_mfma_f32_16x16x32_bf16 v[84:87], v[232:235], v[202:205], v[84:87]
	v_mfma_f32_16x16x32_bf16 v[76:79], v[240:243], v[202:205], v[76:79]
	v_mfma_f32_16x16x32_bf16 v[68:71], v[232:235], v[210:213], v[68:71]
	v_mfma_f32_16x16x32_bf16 v[64:67], v[240:243], v[210:213], v[64:67]
	s_mov_b32 m0, s7
	v_lshl_add_u64 v[244:245], s[48:49], 0, v[132:133]
	s_barrier
	ds_read_b128 v[160:163], v143 offset:16384
	ds_read_b128 v[164:167], v143 offset:17408
	ds_read_b128 v[168:171], v143 offset:18432
	ds_read_b128 v[172:175], v143 offset:19456
	ds_read_b128 v[198:201], v143 offset:20480
	ds_read_b128 v[202:205], v143 offset:21504
	ds_read_b128 v[206:209], v143 offset:22528
	ds_read_b128 v[210:213], v143 offset:23552
	global_load_lds_dwordx4 v[244:245], off
	v_lshl_add_u64 v[246:247], s[48:49], 0, v[130:131]
	s_mov_b32 m0, s9
	s_nop 0
	global_load_lds_dwordx4 v[246:247], off
	s_barrier
	s_waitcnt lgkmcnt(0)
	s_waitcnt lgkmcnt(0)
	v_mfma_f32_16x16x32_bf16 v[60:63], v[144:147], v[160:163], v[60:63]
	v_mfma_f32_16x16x32_bf16 v[56:59], v[152:155], v[160:163], v[56:59]
	v_mfma_f32_16x16x32_bf16 v[52:55], v[144:147], v[168:171], v[52:55]
	v_mfma_f32_16x16x32_bf16 v[44:47], v[152:155], v[168:171], v[44:47]
	v_mfma_f32_16x16x32_bf16 v[36:39], v[144:147], v[198:201], v[36:39]
	v_mfma_f32_16x16x32_bf16 v[28:31], v[152:155], v[198:201], v[28:31]
	v_mfma_f32_16x16x32_bf16 v[20:23], v[144:147], v[206:209], v[20:23]
	v_mfma_f32_16x16x32_bf16 v[12:15], v[152:155], v[206:209], v[12:15]
	v_mfma_f32_16x16x32_bf16 v[60:63], v[148:151], v[164:167], v[60:63]
	v_mfma_f32_16x16x32_bf16 v[56:59], v[156:159], v[164:167], v[56:59]
	v_mfma_f32_16x16x32_bf16 v[52:55], v[148:151], v[172:175], v[52:55]
	v_mfma_f32_16x16x32_bf16 v[44:47], v[156:159], v[172:175], v[44:47]
	v_mfma_f32_16x16x32_bf16 v[36:39], v[148:151], v[202:205], v[36:39]
	v_mfma_f32_16x16x32_bf16 v[28:31], v[156:159], v[202:205], v[28:31]
	v_mfma_f32_16x16x32_bf16 v[20:23], v[148:151], v[210:213], v[20:23]
	v_mfma_f32_16x16x32_bf16 v[12:15], v[156:159], v[210:213], v[12:15]
	s_barrier
	s_add_u32 s20, s28, 0x40000
	s_addc_u32 s21, s29, 0
	s_add_i32 s60, s61, s6
	v_lshl_add_u64 v[144:145], s[20:21], 0, v[176:177]
	s_mov_b32 m0, s60
	s_nop 0
	global_load_lds_dwordx4 v[144:145], off
	v_lshl_add_u64 v[144:145], s[20:21], 0, v[128:129]
	s_add_i32 m0, s60, 0x2000
	s_nop 0
	global_load_lds_dwordx4 v[144:145], off
	s_waitcnt vmcnt(6)
	s_barrier
	v_mfma_f32_16x16x32_bf16 v[48:51], v[214:217], v[160:163], v[48:51]
	v_mfma_f32_16x16x32_bf16 v[40:43], v[236:239], v[160:163], v[40:43]
	v_mfma_f32_16x16x32_bf16 v[32:35], v[214:217], v[168:171], v[32:35]
	v_mfma_f32_16x16x32_bf16 v[24:27], v[236:239], v[168:171], v[24:27]
	v_mfma_f32_16x16x32_bf16 v[16:19], v[214:217], v[198:201], v[16:19]
	v_mfma_f32_16x16x32_bf16 v[8:11], v[236:239], v[198:201], v[8:11]
	v_mfma_f32_16x16x32_bf16 v[4:7], v[214:217], v[206:209], v[4:7]
	v_mfma_f32_16x16x32_bf16 v[0:3], v[236:239], v[206:209], v[0:3]
	v_mfma_f32_16x16x32_bf16 v[48:51], v[232:235], v[164:167], v[48:51]
	v_mfma_f32_16x16x32_bf16 v[40:43], v[240:243], v[164:167], v[40:43]
	v_mfma_f32_16x16x32_bf16 v[32:35], v[232:235], v[172:175], v[32:35]
	v_mfma_f32_16x16x32_bf16 v[24:27], v[240:243], v[172:175], v[24:27]
	v_mfma_f32_16x16x32_bf16 v[16:19], v[232:235], v[202:205], v[16:19]
	v_mfma_f32_16x16x32_bf16 v[8:11], v[240:243], v[202:205], v[8:11]
	v_mfma_f32_16x16x32_bf16 v[4:7], v[232:235], v[210:213], v[4:7]
	v_mfma_f32_16x16x32_bf16 v[0:3], v[240:243], v[210:213], v[0:3]
	s_add_i32 s60, 0, 0x18000
	v_add_u32_e32 v156, s60, v141
	s_barrier
	ds_read_b128 v[144:147], v156
	ds_read_b128 v[148:151], v156 offset:1024
	ds_read_b128 v[152:155], v156 offset:2048
	ds_read_b128 v[156:159], v156 offset:3072
	s_add_u32 s20, s48, 0x40000
	s_addc_u32 s21, s49, 0
	s_mov_b32 m0, s15
	v_lshl_add_u64 v[214:215], s[20:21], 0, v[132:133]
	ds_read_b128 v[160:163], v143 offset:32768
	ds_read_b128 v[164:167], v143 offset:33792
	ds_read_b128 v[168:171], v143 offset:34816
	ds_read_b128 v[172:175], v143 offset:35840
	ds_read_b128 v[198:201], v143 offset:36864
	ds_read_b128 v[202:205], v143 offset:37888
	ds_read_b128 v[206:209], v143 offset:38912
	ds_read_b128 v[210:213], v143 offset:39936
	global_load_lds_dwordx4 v[214:215], off
	v_lshl_add_u64 v[214:215], s[20:21], 0, v[130:131]
	s_mov_b32 m0, s34
	s_nop 0
	global_load_lds_dwordx4 v[214:215], off
	s_waitcnt lgkmcnt(8)
	s_barrier
	s_waitcnt lgkmcnt(0)
	s_waitcnt lgkmcnt(0)
	v_mfma_f32_16x16x32_bf16 v[124:127], v[144:147], v[160:163], v[124:127]
	v_mfma_f32_16x16x32_bf16 v[120:123], v[152:155], v[160:163], v[120:123]
	v_mfma_f32_16x16x32_bf16 v[116:119], v[144:147], v[168:171], v[116:119]
	v_mfma_f32_16x16x32_bf16 v[108:111], v[152:155], v[168:171], v[108:111]
	v_mfma_f32_16x16x32_bf16 v[100:103], v[144:147], v[198:201], v[100:103]
	v_mfma_f32_16x16x32_bf16 v[92:95], v[152:155], v[198:201], v[92:95]
	v_mfma_f32_16x16x32_bf16 v[80:83], v[144:147], v[206:209], v[80:83]
	v_mfma_f32_16x16x32_bf16 v[72:75], v[152:155], v[206:209], v[72:75]
	v_mfma_f32_16x16x32_bf16 v[124:127], v[148:151], v[164:167], v[124:127]
	v_mfma_f32_16x16x32_bf16 v[120:123], v[156:159], v[164:167], v[120:123]
	v_mfma_f32_16x16x32_bf16 v[116:119], v[148:151], v[172:175], v[116:119]
	v_mfma_f32_16x16x32_bf16 v[108:111], v[156:159], v[172:175], v[108:111]
	v_mfma_f32_16x16x32_bf16 v[100:103], v[148:151], v[202:205], v[100:103]
	v_mfma_f32_16x16x32_bf16 v[92:95], v[156:159], v[202:205], v[92:95]
	v_mfma_f32_16x16x32_bf16 v[80:83], v[148:151], v[210:213], v[80:83]
	v_mfma_f32_16x16x32_bf16 v[72:75], v[156:159], v[210:213], v[72:75]
	s_barrier
	s_add_i32 s48, 0, 0x1c000
	s_add_i32 s20, s60, s6
	v_add_u32_e32 v184, s48, v141
	v_lshl_add_u64 v[138:139], v[138:139], 0, s[52:53]
	s_mov_b32 m0, s20
	ds_read_b128 v[214:217], v184
	ds_read_b128 v[232:235], v184 offset:1024
	ds_read_b128 v[236:239], v184 offset:2048
	ds_read_b128 v[240:243], v184 offset:3072
	global_load_lds_dwordx4 v[138:139], off
	v_lshl_add_u64 v[138:139], v[218:219], 0, s[52:53]
	s_add_i32 m0, s20, 0x2000
	s_nop 0
	global_load_lds_dwordx4 v[138:139], off
	s_barrier
	s_waitcnt lgkmcnt(0)
	s_waitcnt lgkmcnt(0)
	v_mfma_f32_16x16x32_bf16 v[112:115], v[214:217], v[160:163], v[112:115]
	v_mfma_f32_16x16x32_bf16 v[104:107], v[236:239], v[160:163], v[104:107]
	v_mfma_f32_16x16x32_bf16 v[96:99], v[214:217], v[168:171], v[96:99]
	v_mfma_f32_16x16x32_bf16 v[88:91], v[236:239], v[168:171], v[88:91]
	v_mfma_f32_16x16x32_bf16 v[84:87], v[214:217], v[198:201], v[84:87]
	v_mfma_f32_16x16x32_bf16 v[76:79], v[236:239], v[198:201], v[76:79]
	v_mfma_f32_16x16x32_bf16 v[68:71], v[214:217], v[206:209], v[68:71]
	v_mfma_f32_16x16x32_bf16 v[64:67], v[236:239], v[206:209], v[64:67]
	v_mfma_f32_16x16x32_bf16 v[112:115], v[232:235], v[164:167], v[112:115]
	v_mfma_f32_16x16x32_bf16 v[104:107], v[240:243], v[164:167], v[104:107]
	v_mfma_f32_16x16x32_bf16 v[96:99], v[232:235], v[172:175], v[96:99]
	v_mfma_f32_16x16x32_bf16 v[88:91], v[240:243], v[172:175], v[88:91]
	v_mfma_f32_16x16x32_bf16 v[84:87], v[232:235], v[202:205], v[84:87]
	v_mfma_f32_16x16x32_bf16 v[76:79], v[240:243], v[202:205], v[76:79]
	v_mfma_f32_16x16x32_bf16 v[68:71], v[232:235], v[210:213], v[68:71]
	v_mfma_f32_16x16x32_bf16 v[64:67], v[240:243], v[210:213], v[64:67]
	s_mov_b32 m0, s51
	v_lshl_add_u64 v[138:139], v[244:245], 0, s[52:53]
	s_barrier
	ds_read_b128 v[160:163], v143 offset:49152
	ds_read_b128 v[164:167], v143 offset:50176
	ds_read_b128 v[168:171], v143 offset:51200
	ds_read_b128 v[172:175], v143 offset:52224
	ds_read_b128 v[198:201], v143 offset:53248
	ds_read_b128 v[202:205], v143 offset:54272
	ds_read_b128 v[206:209], v143 offset:55296
	ds_read_b128 v[210:213], v143 offset:56320
	global_load_lds_dwordx4 v[138:139], off
	v_lshl_add_u64 v[138:139], v[246:247], 0, s[52:53]
	s_mov_b32 m0, s54
	s_nop 0
	global_load_lds_dwordx4 v[138:139], off
	s_barrier
	s_waitcnt lgkmcnt(0)
	s_waitcnt lgkmcnt(0)
	v_mfma_f32_16x16x32_bf16 v[60:63], v[144:147], v[160:163], v[60:63]
	v_mfma_f32_16x16x32_bf16 v[56:59], v[152:155], v[160:163], v[56:59]
	v_mfma_f32_16x16x32_bf16 v[52:55], v[144:147], v[168:171], v[52:55]
	v_mfma_f32_16x16x32_bf16 v[44:47], v[152:155], v[168:171], v[44:47]
	v_mfma_f32_16x16x32_bf16 v[36:39], v[144:147], v[198:201], v[36:39]
	v_mfma_f32_16x16x32_bf16 v[28:31], v[152:155], v[198:201], v[28:31]
	v_mfma_f32_16x16x32_bf16 v[20:23], v[144:147], v[206:209], v[20:23]
	v_mfma_f32_16x16x32_bf16 v[12:15], v[152:155], v[206:209], v[12:15]
	v_mfma_f32_16x16x32_bf16 v[60:63], v[148:151], v[164:167], v[60:63]
	v_mfma_f32_16x16x32_bf16 v[56:59], v[156:159], v[164:167], v[56:59]
	v_mfma_f32_16x16x32_bf16 v[52:55], v[148:151], v[172:175], v[52:55]
	v_mfma_f32_16x16x32_bf16 v[44:47], v[156:159], v[172:175], v[44:47]
	v_mfma_f32_16x16x32_bf16 v[36:39], v[148:151], v[202:205], v[36:39]
	v_mfma_f32_16x16x32_bf16 v[28:31], v[156:159], v[202:205], v[28:31]
	v_mfma_f32_16x16x32_bf16 v[20:23], v[148:151], v[210:213], v[20:23]
	v_mfma_f32_16x16x32_bf16 v[12:15], v[156:159], v[210:213], v[12:15]
	s_barrier
	s_add_u32 s20, s28, 0x40080
	s_addc_u32 s21, s29, 0
	s_add_i32 s28, s48, s6
	v_lshl_add_u64 v[138:139], s[20:21], 0, v[176:177]
	s_mov_b32 m0, s28
	s_nop 0
	global_load_lds_dwordx4 v[138:139], off
	v_lshl_add_u64 v[138:139], s[20:21], 0, v[128:129]
	s_add_i32 m0, s28, 0x2000
	s_nop 0
	global_load_lds_dwordx4 v[138:139], off
	s_waitcnt vmcnt(6)
	s_barrier
	v_mfma_f32_16x16x32_bf16 v[48:51], v[214:217], v[160:163], v[48:51]
	v_mfma_f32_16x16x32_bf16 v[40:43], v[236:239], v[160:163], v[40:43]
	v_mfma_f32_16x16x32_bf16 v[32:35], v[214:217], v[168:171], v[32:35]
	v_mfma_f32_16x16x32_bf16 v[24:27], v[236:239], v[168:171], v[24:27]
	v_mfma_f32_16x16x32_bf16 v[16:19], v[214:217], v[198:201], v[16:19]
	v_mfma_f32_16x16x32_bf16 v[8:11], v[236:239], v[198:201], v[8:11]
	v_mfma_f32_16x16x32_bf16 v[4:7], v[214:217], v[206:209], v[4:7]
	v_mfma_f32_16x16x32_bf16 v[0:3], v[236:239], v[206:209], v[0:3]
	v_mfma_f32_16x16x32_bf16 v[48:51], v[232:235], v[164:167], v[48:51]
	v_mfma_f32_16x16x32_bf16 v[40:43], v[240:243], v[164:167], v[40:43]
	v_mfma_f32_16x16x32_bf16 v[32:35], v[232:235], v[172:175], v[32:35]
	v_mfma_f32_16x16x32_bf16 v[24:27], v[240:243], v[172:175], v[24:27]
	v_mfma_f32_16x16x32_bf16 v[16:19], v[232:235], v[202:205], v[16:19]
	v_mfma_f32_16x16x32_bf16 v[8:11], v[240:243], v[202:205], v[8:11]
	v_mfma_f32_16x16x32_bf16 v[4:7], v[232:235], v[210:213], v[4:7]
	v_mfma_f32_16x16x32_bf16 v[0:3], v[240:243], v[210:213], v[0:3]
	s_add_i32 vcc_lo, vcc_lo, 2
	s_add_u32 s46, s46, 0x100
	s_addc_u32 s47, s47, 0
	s_add_u32 s58, s58, 0x100
	s_addc_u32 s59, s59, 0
	s_cmp_gt_u32 vcc_lo, 13
	s_barrier
	s_cbranch_scc0 .LBB0_292
	v_lshl_add_u32 v144, s57, 8, v140
	v_lshl_or_b32 v138, s2, 8, v142
	v_ashrrev_i32_e32 v145, 31, v144
	v_readlane_b32 s20, v254, 43
	v_ashrrev_i32_e32 v139, 31, v138
	v_lshlrev_b64 v[146:147], 16, v[144:145]
	v_readlane_b32 s21, v254, 44
	v_lshlrev_b64 v[148:149], 1, v[138:139]
	v_cvt_pk_bf16_f32 v124, v124, v125
	v_cvt_pk_bf16_f32 v125, v126, v127
	v_cvt_pk_bf16_f32 v126, v120, v121
	v_cvt_pk_bf16_f32 v127, v122, v123
	s_nop 0
	v_lshl_add_u64 v[146:147], s[20:21], 0, v[146:147]
	v_lshl_add_u64 v[138:139], v[146:147], 0, v[148:149]
	global_store_dwordx4 v[138:139], v[124:127], off
	v_cvt_pk_bf16_f32 v112, v112, v113
	v_cvt_pk_bf16_f32 v113, v114, v115
	v_cvt_pk_bf16_f32 v114, v104, v105
	v_or_b32_e32 v104, 16, v144
	v_ashrrev_i32_e32 v105, 31, v104
	v_lshlrev_b64 v[104:105], 16, v[104:105]
	v_lshl_add_u64 v[104:105], s[20:21], 0, v[104:105]
	v_cvt_pk_bf16_f32 v115, v106, v107
	global_store_dwordx4 v[138:139], v[112:115], off offset:256
	s_mov_b32 s1, 0x900000
	s_mov_b32 s2, s0
	v_lshl_add_u64 v[112:113], v[104:105], 0, v[148:149]
	v_cvt_pk_bf16_f32 v104, v116, v117
	v_cvt_pk_bf16_f32 v105, v118, v119
	v_cvt_pk_bf16_f32 v106, v108, v109
	v_cvt_pk_bf16_f32 v107, v110, v111
	global_store_dwordx4 v[112:113], v[104:107], off
	v_cvt_pk_bf16_f32 v96, v96, v97
	v_cvt_pk_bf16_f32 v97, v98, v99
	v_cvt_pk_bf16_f32 v98, v88, v89
	v_or_b32_e32 v88, 32, v144
	v_ashrrev_i32_e32 v89, 31, v88
	v_lshlrev_b64 v[88:89], 16, v[88:89]
	v_lshl_add_u64 v[88:89], s[20:21], 0, v[88:89]
	v_cvt_pk_bf16_f32 v99, v90, v91
	global_store_dwordx4 v[112:113], v[96:99], off offset:256
	s_mov_b32 s57, s40
	s_mov_b64 s[28:29], s[44:45]
	v_lshl_add_u64 v[96:97], v[88:89], 0, v[148:149]
	v_cvt_pk_bf16_f32 v88, v100, v101
	v_cvt_pk_bf16_f32 v89, v102, v103
	v_cvt_pk_bf16_f32 v90, v92, v93
	v_cvt_pk_bf16_f32 v91, v94, v95
	global_store_dwordx4 v[96:97], v[88:91], off
	v_cvt_pk_bf16_f32 v84, v84, v85
	v_cvt_pk_bf16_f32 v85, v86, v87
	v_cvt_pk_bf16_f32 v86, v76, v77
	v_or_b32_e32 v76, 48, v144
	v_ashrrev_i32_e32 v77, 31, v76
	v_lshlrev_b64 v[76:77], 16, v[76:77]
	v_lshl_add_u64 v[76:77], s[20:21], 0, v[76:77]
	v_cvt_pk_bf16_f32 v87, v78, v79
	global_store_dwordx4 v[96:97], v[84:87], off offset:256
	s_mov_b64 s[20:21], 0x800000
	s_mov_b64 s[46:47], s[42:43]
	v_lshl_add_u64 v[84:85], v[76:77], 0, v[148:149]
	v_cvt_pk_bf16_f32 v76, v80, v81
	v_cvt_pk_bf16_f32 v77, v82, v83
	v_cvt_pk_bf16_f32 v78, v72, v73
	v_cvt_pk_bf16_f32 v79, v74, v75
	global_store_dwordx4 v[84:85], v[76:79], off
	v_cvt_pk_bf16_f32 v68, v68, v69
	v_cvt_pk_bf16_f32 v69, v70, v71
	v_cvt_pk_bf16_f32 v70, v64, v65
	v_cvt_pk_bf16_f32 v71, v66, v67
	global_store_dwordx4 v[84:85], v[68:71], off offset:256
	v_cvt_pk_bf16_f32 v60, v60, v61
	v_cvt_pk_bf16_f32 v61, v62, v63
	v_cvt_pk_bf16_f32 v62, v56, v57
	v_add_co_u32_e32 v56, vcc, s23, v138
	v_lshl_add_u64 v[64:65], v[138:139], 0, s[20:21]
	s_nop 0
	v_addc_co_u32_e32 v57, vcc, 0, v139, vcc
	v_cvt_pk_bf16_f32 v63, v58, v59
	global_store_dwordx4 v[56:57], v[60:63], off
	v_cvt_pk_bf16_f32 v48, v48, v49
	v_cvt_pk_bf16_f32 v49, v50, v51
	v_cvt_pk_bf16_f32 v50, v40, v41
	v_cvt_pk_bf16_f32 v51, v42, v43
	global_store_dwordx4 v[64:65], v[48:51], off offset:256
	s_mov_b64 s[20:21], 0x900000
	v_cvt_pk_bf16_f32 v40, v52, v53
	v_cvt_pk_bf16_f32 v41, v54, v55
	v_cvt_pk_bf16_f32 v42, v44, v45
	v_add_co_u32_e32 v44, vcc, s1, v138
	v_lshl_add_u64 v[48:49], v[138:139], 0, s[20:21]
	s_nop 0
	v_addc_co_u32_e32 v45, vcc, 0, v139, vcc
	s_mov_b32 s1, 0xa00000
	v_cvt_pk_bf16_f32 v43, v46, v47
	global_store_dwordx4 v[44:45], v[40:43], off
	v_cvt_pk_bf16_f32 v32, v32, v33
	v_cvt_pk_bf16_f32 v33, v34, v35
	v_cvt_pk_bf16_f32 v34, v24, v25
	v_cvt_pk_bf16_f32 v35, v26, v27
	global_store_dwordx4 v[48:49], v[32:35], off offset:256
	s_mov_b64 s[20:21], 0xa00000
	v_cvt_pk_bf16_f32 v24, v36, v37
	v_cvt_pk_bf16_f32 v25, v38, v39
	v_cvt_pk_bf16_f32 v26, v28, v29
	v_add_co_u32_e32 v28, vcc, s1, v138
	v_lshl_add_u64 v[32:33], v[138:139], 0, s[20:21]
	s_nop 0
	v_addc_co_u32_e32 v29, vcc, 0, v139, vcc
	s_mov_b32 s1, 0xb00000
	v_cvt_pk_bf16_f32 v27, v30, v31
	global_store_dwordx4 v[28:29], v[24:27], off
	v_cvt_pk_bf16_f32 v16, v16, v17
	v_cvt_pk_bf16_f32 v17, v18, v19
	v_cvt_pk_bf16_f32 v18, v8, v9
	v_cvt_pk_bf16_f32 v19, v10, v11
	global_store_dwordx4 v[32:33], v[16:19], off offset:256
	v_cvt_pk_bf16_f32 v8, v20, v21
	v_cvt_pk_bf16_f32 v9, v22, v23
	v_cvt_pk_bf16_f32 v10, v12, v13
	v_add_co_u32_e32 v12, vcc, s1, v138
	s_mov_b64 s[20:21], 0xb00000
	s_nop 0
	v_addc_co_u32_e32 v13, vcc, 0, v139, vcc
	v_lshl_add_u64 v[16:17], v[138:139], 0, s[20:21]
	s_and_b64 vcc, exec, s[38:39]
	v_cvt_pk_bf16_f32 v11, v14, v15
	global_store_dwordx4 v[12:13], v[8:11], off
	v_cvt_pk_bf16_f32 v4, v4, v5
	v_cvt_pk_bf16_f32 v5, v6, v7
	v_cvt_pk_bf16_f32 v6, v0, v1
	v_cvt_pk_bf16_f32 v7, v2, v3
	global_store_dwordx4 v[16:17], v[4:7], off offset:256
	s_cbranch_vccz .LBB0_285
	s_waitcnt vmcnt(0)
	v_readlane_b32 s54, v253, 37
	s_cmpk_gt_u32 s3, 0xff
	v_readlane_b32 s55, v253, 38
	s_cbranch_scc1 .LBB0_296
	s_barrier
